# gla_out item: the 2x17 low-rank gate weight and bias loads of both directions are requested at the item head into spare registers and copied at the original wait; otherwise as previous
# baseline (speedup 1.0000x reference)
; __device__ __forceinline__ void gla_decay(unsigned char* lds, const float* glow_t0, const float* Wg  , const float* bg  , int dir) {
;     float* Bs = (float*)(lds + GL_BS); float* Tot = (float*)(lds + GL_TOT); float* GLs = (float*)(lds + GL_O);
;     int tid_ = threadIdx.x; asm volatile("" : "+v"(tid_)); const int tid = tid_;
;     { const int s = tid >> 3, q = tid & 7;
;       const float* gp = glow_t0 + (size_t)s * 32 + dir * 16 + q * 2;
;       GLs[s * 16 + q * 2] = gp[0]; GLs[s * 16 + q * 2 + 1] = gp[1]; }
;     const int d = tid & 63, seg = tid >> 6;
;     float w[16];
; #pragma unroll
;     for (int r = 0; r < 16; ++r) w[r] = Wg[r * 256 + d];
;     const float bias = bg[d];
; __device__ __forceinline__ void gla_out_item(unsigned char* lds, unsigned char* ws, const float* wgate, const float* bgate, const float* hnorm, int l, int item, bool dowrite = true) {
;     const int c = item % 132, h = (item / 132) & 3, b = item / 528;
;     const int t0 = b * TB + c * 64;
;     int tid_ = threadIdx.x; asm volatile("" : "+v"(tid_));
;     const int tid = tid_, lane = tid & 63, wid = tid >> 6, ql = lane & 15, g = lane >> 4;
;     const float* Bs = (const float*)(lds + GL_BS);
;     bf16_t* QE = (bf16_t*)(lds + GL_QE); bf16_t* KE = (bf16_t*)(lds + GL_KE); bf16_t* ATT = (bf16_t*)(lds + GL_ATT); const bf16_t* Vt = (const bf16_t*)(lds + GL_VT);
;     const u32x4 qraw = *(const u32x4*)((const bf16_t*)(ws + O_CQ) + (size_t)(t0 + (tid >> 3)) * 256 + h * 64 + (tid & 7) * 8);
;     const u32x4 kraw = *(const u32x4*)((const bf16_t*)(ws + O_CK) + (size_t)(t0 + (tid >> 3)) * 256 + h * 64 + (tid & 7) * 8);
;     bf16x8 sfr[2][2];
; #pragma unroll
;     for (int dd = 0; dd < 2; ++dd)
; #pragma unroll
;         for (int kk = 0; kk < 2; ++kk) sfr[dd][kk] = *(const bf16x8*)((const bf16_t*)(ws + O_ST) + (size_t)(((b * 4 + h) * 2 + dd) * 132 + c) * 8192 + (wid * 16 + ql) * 64 + kk * 32 + g * 8);
;     const u32x4 rraw0 = *(const u32x4*)((const bf16_t*)(ws + O_CR) + (size_t)(t0 + (tid >> 3)) * 512 + h * 128 + (tid & 7) * 16);
;     const u32x4 rraw1 = *(const u32x4*)((const bf16_t*)(ws + O_CR) + (size_t)(t0 + (tid >> 3)) * 512 + h * 128 + (tid & 7) * 16 + 8);
;     gla_load_vt(lds, (const bf16_t*)(ws + O_CV) + (size_t)t0 * 512 + h * 128);
.Lgo_map:
	s_lshl_b32 s37, s51, 6
	s_mul_hi_i32 s0, s51, 0x3e0f83e1
	s_ashr_i32 s1, s0, 5
	s_lshr_b32 s18, s0, 31
	s_ashr_i32 s0, s0, 7
	s_add_i32 s1, s1, s18
	s_add_i32 s18, s0, s18
	s_waitcnt vmcnt(0)
	v_mov_b32_e32 v68, v203
	s_mul_i32 s38, s18, 0x2100
	s_mul_i32 s19, s1, 0x84
	v_ashrrev_i32_e32 v37, 3, v68
	s_and_b32 s52, s1, 3
	s_mulk_i32 s1, 0x2100
	v_add_u32_e32 v0, s38, v37
	v_subrev_u32_e32 v0, s1, v0
	v_add_u32_e32 v0, s37, v0
	v_ashrrev_i32_e32 v1, 31, v0
	v_lshlrev_b64 v[2:3], 9, v[0:1]
	s_sub_i32 s0, s38, s1
	v_lshl_add_u64 v[4:5], s[2:3], 0, v[2:3]
	s_lshl_b32 s60, s52, 7
	v_and_b32_e32 v41, 7, v68
	v_lshl_add_u64 v[2:3], s[10:11], 0, v[2:3]
	s_mul_i32 s1, s18, 0x420
	s_mul_i32 s18, s52, 0x108
	v_lshl_add_u64 v[4:5], v[4:5], 0, s[60:61]
	v_lshlrev_b32_e32 v34, 4, v41
	v_mov_b32_e32 v35, v36
	v_lshl_add_u64 v[2:3], v[2:3], 0, s[60:61]
	s_add_i32 s1, s1, s18
	v_and_b32_e32 v69, 15, v68
	v_lshl_add_u64 v[4:5], v[4:5], 0, v[34:35]
	v_lshl_add_u64 v[2:3], v[2:3], 0, v[34:35]
	s_sub_i32 s1, s1, s19
	v_ashrrev_i32_e32 v55, 6, v68
	global_load_dwordx4 v[24:27], v[4:5], off
	global_load_dwordx4 v[20:23], v[2:3], off
	v_lshlrev_b32_e32 v2, 6, v69
	s_add_i32 s18, s51, s1
	v_lshl_or_b32 v2, v55, 10, v2
	s_ashr_i32 s19, s18, 31
	v_bfe_u32 v70, v68, 4, 2
	v_ashrrev_i32_e32 v3, 31, v2
	s_lshl_b64 s[38:39], s[18:19], 14
	s_addk_i32 s18, 0x84
	s_add_i32 s0, s37, s0
	v_lshl_add_u64 v[2:3], v[2:3], 1, s[20:21]
	v_lshlrev_b32_e32 v38, 4, v70
	v_mov_b32_e32 v39, v36
	s_ashr_i32 s19, s18, 31
	v_lshl_add_u64 v[2:3], v[2:3], 0, v[38:39]
	s_lshl_b64 s[18:19], s[18:19], 14
	v_lshlrev_b64 v[0:1], 10, v[0:1]
	s_ashr_i32 s1, s0, 31
	v_lshl_add_u64 v[4:5], v[2:3], 0, s[38:39]
	v_lshl_add_u64 v[2:3], v[2:3], 0, s[18:19]
	v_lshl_add_u64 v[0:1], s[14:15], 0, v[0:1]
	s_lshl_b32 s60, s52, 8
	s_lshl_b64 s[18:19], s[0:1], 10
	v_lshl_add_u64 v[0:1], v[0:1], 0, s[60:61]
	v_lshlrev_b32_e32 v42, 5, v41
	v_mov_b32_e32 v43, v36
	s_add_u32 s18, s13, s18
	v_lshl_add_u64 v[32:33], v[0:1], 0, v[42:43]
	s_addc_u32 s19, s24, s19
	v_mov_b32_e32 v35, v203
	global_load_dwordx4 v[16:19], v[4:5], off
	global_load_dwordx4 v[28:31], v[4:5], off offset:64
	global_load_dwordx4 v[12:15], v[2:3], off
	global_load_dwordx4 v[8:11], v[2:3], off offset:64
	s_nop 0
	global_load_dwordx4 v[0:3], v[32:33], off offset:16
	global_load_dwordx4 v[4:7], v[32:33], off
	s_add_u32 s18, s18, s60
	s_addc_u32 s19, s19, 0
	v_and_b32_e32 v39, 63, v35
	v_lshlrev_b32_e32 v48, 10, v39
	v_mov_b32_e32 v49, v36
	v_lshl_add_u32 v54, v39, 1, 0
	v_ashrrev_i32_e32 v39, 3, v35
	v_lshl_add_u64 v[52:53], s[18:19], 0, v[48:49]
	v_and_b32_e32 v48, -8, v39
	v_ashrrev_i32_e32 v49, 31, v48
	v_lshl_add_u64 v[50:51], v[48:49], 1, v[52:53]
	v_mad_u64_u32 v[56:57], s[18:19], v48, s76, v[54:55]
	global_load_dwordx4 v[48:51], v[50:51], off
	v_add_u32_e32 v35, 0x200, v35
	v_ashrrev_i32_e32 v35, 3, v35
	s_lshl_b64 s[0:1], s[0:1], 7
	s_add_u32 s42, s25, s0
	v_add_u32_e32 v42, 0, v42
	s_addc_u32 s43, s26, s1
	v_and_b32_e32 v120, -8, v35
	v_ashrrev_i32_e32 v121, 31, v120
	v_lshl_add_u64 v[120:121], v[120:121], 1, v[52:53]
	global_load_dwordx4 v[116:119], v[120:121], off
	v_ashrrev_i32_e32 v124, 3, v203
	v_ashrrev_i32_e32 v125, 31, v124
	v_lshlrev_b64 v[126:127], 7, v[124:125]
	v_lshl_add_u64 v[126:127], s[42:43], 0, v[126:127]
	v_lshlrev_b32_e32 v128, 3, v203
	v_and_b32_e32 v128, 56, v128
	v_mov_b32_e32 v129, v36
	v_lshl_add_u64 v[126:127], v[126:127], 0, v[128:129]
	global_load_dwordx2 v[130:131], v[126:127], off
	global_load_dwordx2 v[132:133], v[126:127], off offset:64
	v_sub_u32_e32 v34, v42, v34
	v_add_u32_e32 v66, 0, v38
	s_add_u32 s48, s44, s60
	s_addc_u32 s49, s45, 0
	s_add_u32 s53, s46, s60
	s_addc_u32 s54, s47, 0
	s_add_u32 s92, s48, s16
	s_addc_u32 s93, s49, s17
	s_add_u32 s94, s48, s28
	s_addc_u32 s95, s49, s29
	s_add_u32 s88, s53, s30
	s_addc_u32 s89, s54, s31
	s_add_u32 s90, s53, s34
	s_addc_u32 s91, s54, s35
	v_lshlrev_b32_e32 v176, 2, v203
	v_and_b32_e32 v176, 0xfc, v176
	v_add_u32_e32 v177, 0x1000, v176
	v_add_u32_e32 v178, 0x2000, v176
	v_add_u32_e32 v179, 0x3000, v176
	global_load_dword v142, v176, s[92:93]
	global_load_dword v143, v176, s[92:93] offset:1024
	global_load_dword v144, v176, s[92:93] offset:2048
	global_load_dword v145, v176, s[92:93] offset:3072
	global_load_dword v146, v177, s[92:93]
	global_load_dword v147, v177, s[92:93] offset:1024
	global_load_dword v148, v177, s[92:93] offset:2048
	global_load_dword v149, v177, s[92:93] offset:3072
	global_load_dword v150, v178, s[92:93]
	global_load_dword v151, v178, s[92:93] offset:1024
	global_load_dword v152, v178, s[92:93] offset:2048
	global_load_dword v153, v178, s[92:93] offset:3072
	global_load_dword v154, v179, s[92:93]
	global_load_dword v155, v179, s[92:93] offset:1024
	global_load_dword v156, v179, s[92:93] offset:2048
	global_load_dword v157, v179, s[92:93] offset:3072
	global_load_dword v158, v176, s[88:89]
	global_load_dword v159, v176, s[94:95]
	global_load_dword v160, v176, s[94:95] offset:1024
	global_load_dword v161, v176, s[94:95] offset:2048
	global_load_dword v162, v176, s[94:95] offset:3072
	global_load_dword v163, v177, s[94:95]
	global_load_dword v164, v177, s[94:95] offset:1024
	global_load_dword v165, v177, s[94:95] offset:2048
	global_load_dword v166, v177, s[94:95] offset:3072
	global_load_dword v167, v178, s[94:95]
	global_load_dword v168, v178, s[94:95] offset:1024
	global_load_dword v169, v178, s[94:95] offset:2048
	global_load_dword v170, v178, s[94:95] offset:3072
	global_load_dword v171, v179, s[94:95]
	global_load_dword v172, v179, s[94:95] offset:1024
	global_load_dword v173, v179, s[94:95] offset:2048
	global_load_dword v174, v179, s[94:95] offset:3072
	global_load_dword v175, v176, s[90:91]
	s_waitcnt vmcnt(0)
; __device__ __forceinline__ void gla_decay(unsigned char* lds, const float* glow_t0, const float* Wg  , const float* bg  , int dir) {
;     float* Bs = (float*)(lds + GL_BS); float* Tot = (float*)(lds + GL_TOT); float* GLs = (float*)(lds + GL_O);
;     int tid_ = threadIdx.x; asm volatile("" : "+v"(tid_)); const int tid = tid_;
;     { const int s = tid >> 3, q = tid & 7;
;       const float* gp = glow_t0 + (size_t)s * 32 + dir * 16 + q * 2;
;       GLs[s * 16 + q * 2] = gp[0]; GLs[s * 16 + q * 2 + 1] = gp[1]; }
;     const int d = tid & 63, seg = tid >> 6;
;     float w[16];
; #pragma unroll
;     for (int r = 0; r < 16; ++r) w[r] = Wg[r * 256 + d];
;     const float bias = bg[d];
;     __syncthreads();
;     float loc[8];
; #pragma unroll
;     for (int k = 0; k < 8; ++k) { const float* gl = GLs + (seg * 8 + k) * 16; float a = bias;
; #pragma unroll
;         for (int r = 0; r < 16; ++r) a += gl[r] * w[r];
;         loc[k] = (fminf(a, 0.f) - __logf(1.f + __expf(-fabsf(a)))) * (1.f / 16.f); }
; __device__ __forceinline__ void gla_load_vt(unsigned char* lds, const bf16_t* cv_t0  ) {
;     ...
;     for (int r = 0; r < 2; ++r) { const int ci = tid + 512 * r, s = ci & 63, eg = ci >> 6;
;         const u32x4 w = *(const u32x4*)(cv_t0 + (size_t)s * 512 + eg * 8);
;         bf16_t* dst = Vt + (eg * 8) * 72 + s;
;         dst[0 * 72] = (bf16_t)(w.x & 0xffffu); dst[1 * 72] = (bf16_t)(w.x >> 16); dst[2 * 72] = (bf16_t)(w.y & 0xffffu); dst[3 * 72] = (bf16_t)(w.y >> 16);
;         dst[4 * 72] = (bf16_t)(w.z & 0xffffu); dst[5 * 72] = (bf16_t)(w.z >> 16); dst[6 * 72] = (bf16_t)(w.w & 0xffffu); dst[7 * 72] = (bf16_t)(w.w >> 16); }
	ds_write_b16 v56, v48 offset:46336
	ds_write_b16_d16_hi v56, v48 offset:46480
	ds_write_b16 v56, v49 offset:46624
	ds_write_b16_d16_hi v56, v49 offset:46768
	ds_write_b16 v56, v50 offset:46912
	ds_write_b16_d16_hi v56, v50 offset:47056
	ds_write_b16 v56, v51 offset:47200
	ds_write_b16_d16_hi v56, v51 offset:47344
	v_and_b32_e32 v48, -8, v35
	v_ashrrev_i32_e32 v49, 31, v48
	v_mad_u64_u32 v[52:53], s[18:19], v48, s76, v[54:55]
	s_add_u32 s18, s48, s16
	s_addc_u32 s19, s49, s17
	s_waitcnt vmcnt(0)
	ds_write_b16 v52, v116 offset:46336
	ds_write_b16_d16_hi v52, v116 offset:46480
	ds_write_b16 v52, v117 offset:46624
	ds_write_b16_d16_hi v52, v117 offset:46768
	ds_write_b16 v52, v118 offset:46912
	ds_write_b16_d16_hi v52, v118 offset:47056
	ds_write_b16 v52, v119 offset:47200
	ds_write_b16_d16_hi v52, v119 offset:47344
	v_mad_u64_u32 v[48:49], s[0:1], v37, s56, v[42:43]
	v_mov_b32_e32 v49, v203
	v_mad_u64_u32 v[42:43], s[0:1], v37, s76, v[34:35]
	v_ashrrev_i32_e32 v50, 3, v49
	v_bfi_b32 v35, -16, v37, v68
	v_ashrrev_i32_e32 v51, 31, v50
	v_and_b32_e32 v34, -16, v37
	v_mad_u64_u32 v[38:39], s[0:1], v35, s76, v[66:67]
	v_lshlrev_b64 v[52:53], 7, v[50:51]
	v_lshlrev_b32_e32 v51, 3, v49
	v_lshlrev_b32_e32 v43, 5, v55
	v_lshl_or_b32 v39, v70, 2, v34
	v_lshl_or_b32 v34, v55, 4, v69
	v_lshl_add_u64 v[52:53], s[42:43], 0, v[52:53]
	v_and_b32_e32 v54, 56, v51
	v_mov_b32_e32 v55, v36
	v_lshl_add_u64 v[52:53], v[52:53], 0, v[54:55]
	v_lshlrev_b32_e32 v50, 6, v50
	v_add3_u32 v54, 0, v50, v54
	v_lshlrev_b32_e32 v64, 2, v49
	v_mad_u64_u32 v[34:35], s[0:1], v34, s76, v[66:67]
	s_add_u32 s0, s53, s30
	s_addc_u32 s1, s54, s31
	v_ashrrev_i32_e32 v49, 6, v49
	v_lshl_add_u32 v72, v49, 9, 0
	v_mul_u32_u24_e32 v35, 0x48, v69
	v_lshl_add_u32 v35, v35, 1, v66
	s_waitcnt vmcnt(0)
	ds_write_b64 v54, v[130:131] offset:64768
	v_and_b32_e32 v50, 0xfc, v64
	v_mov_b32_e32 v51, v36
	v_lshl_add_u64 v[52:53], s[18:19], 0, v[50:51]
	v_add_co_u32_e32 v54, vcc, s69, v52
	v_addc_co_u32_e32 v55, vcc, 0, v53, vcc
	v_add_co_u32_e32 v56, vcc, s67, v52
	s_nop 1
	v_addc_co_u32_e32 v57, vcc, 0, v53, vcc
	v_add_co_u32_e32 v52, vcc, s66, v52
	v_addc_co_u32_e32 v53, vcc, 0, v53, vcc
	s_waitcnt lgkmcnt(0)
	s_barrier
	ds_read_b128 v[52:55], v72 offset:65216
	v_add_u32_e32 v50, 0, v50
	s_waitcnt vmcnt(0) lgkmcnt(0)
	v_mov_b32_e32 v51, v142
	v_mov_b32_e32 v65, v143
	v_mov_b32_e32 v67, v144
	v_mov_b32_e32 v71, v145
	v_mov_b32_e32 v76, v146
	v_mov_b32_e32 v77, v147
	v_mov_b32_e32 v78, v148
	v_mov_b32_e32 v79, v149
	v_mov_b32_e32 v80, v150
	v_mov_b32_e32 v81, v151
	v_mov_b32_e32 v82, v152
	v_mov_b32_e32 v83, v153
	v_mov_b32_e32 v84, v154
	v_mov_b32_e32 v85, v155
	v_mov_b32_e32 v86, v156
	v_mov_b32_e32 v87, v157
	v_mov_b32_e32 v88, v158
	v_fma_f32 v56, v51, v52, v88
	v_fmac_f32_e32 v56, v65, v53
	v_fmac_f32_e32 v56, v67, v54
	v_fmac_f32_e32 v56, v71, v55
	ds_read_b128 v[52:55], v72 offset:65232
	s_waitcnt lgkmcnt(0)
	v_fmac_f32_e32 v56, v76, v52
	v_fmac_f32_e32 v56, v77, v53
	v_fmac_f32_e32 v56, v78, v54
	v_fmac_f32_e32 v56, v79, v55
	ds_read_b128 v[52:55], v72 offset:65248
	s_waitcnt lgkmcnt(0)
	v_fmac_f32_e32 v56, v80, v52
	v_fmac_f32_e32 v56, v81, v53
	v_fmac_f32_e32 v56, v82, v54
	v_fmac_f32_e32 v56, v83, v55
	ds_read_b128 v[52:55], v72 offset:65264
	s_waitcnt lgkmcnt(0)
	v_fmac_f32_e32 v56, v84, v52
	v_fmac_f32_e32 v56, v85, v53
	v_fmac_f32_e32 v56, v86, v54
	v_fmac_f32_e32 v56, v87, v55
	v_mul_f32_e64 v53, |v56|, s55
	v_exp_f32_e32 v53, v53
	v_min_f32_e32 v52, 0, v56
	v_add_f32_e32 v53, 1.0, v53
	v_cmp_gt_f32_e32 vcc, s33, v53
	s_nop 1
	v_cndmask_b32_e64 v54, 0, 32, vcc
	v_ldexp_f32 v53, v53, v54
	v_log_f32_e32 v53, v53
	s_nop 0
	v_mul_f32_e32 v54, 0x3f317217, v53
	v_fma_f32 v54, v53, s57, -v54
	v_fmac_f32_e32 v54, 0x3377d1cf, v53
	v_fmac_f32_e32 v54, 0x3f317217, v53
	v_cmp_lt_f32_e64 s[38:39], |v53|, s58
	s_nop 1
	v_cndmask_b32_e64 v53, v53, v54, s[38:39]
	v_cndmask_b32_e32 v54, 0, v229, vcc
	v_sub_f32_e32 v53, v53, v54
	v_sub_f32_e32 v89, v52, v53
	ds_read_b128 v[52:55], v72 offset:65152
	s_waitcnt lgkmcnt(0)
	v_fma_f32 v56, v51, v52, v88
	v_fmac_f32_e32 v56, v65, v53
	v_fmac_f32_e32 v56, v67, v54
	v_fmac_f32_e32 v56, v71, v55
	ds_read_b128 v[52:55], v72 offset:65168
	s_waitcnt lgkmcnt(0)
	v_fmac_f32_e32 v56, v76, v52
	v_fmac_f32_e32 v56, v77, v53
	v_fmac_f32_e32 v56, v78, v54
	v_fmac_f32_e32 v56, v79, v55
	ds_read_b128 v[52:55], v72 offset:65184
	s_waitcnt lgkmcnt(0)
	v_fmac_f32_e32 v56, v80, v52
	v_fmac_f32_e32 v56, v81, v53
	v_fmac_f32_e32 v56, v82, v54
	v_fmac_f32_e32 v56, v83, v55
	ds_read_b128 v[52:55], v72 offset:65200
	s_waitcnt lgkmcnt(0)
	v_fmac_f32_e32 v56, v84, v52
	v_fmac_f32_e32 v56, v85, v53
	v_fmac_f32_e32 v56, v86, v54
	v_fmac_f32_e32 v56, v87, v55
	v_mul_f32_e64 v53, |v56|, s55
	v_exp_f32_e32 v53, v53
	v_min_f32_e32 v52, 0, v56
	v_add_f32_e32 v53, 1.0, v53
	v_cmp_gt_f32_e32 vcc, s33, v53
	s_nop 1
	v_cndmask_b32_e64 v54, 0, 32, vcc
	v_ldexp_f32 v53, v53, v54
	v_log_f32_e32 v53, v53
	s_nop 0
	v_mul_f32_e32 v54, 0x3f317217, v53
	v_fma_f32 v54, v53, s57, -v54
	v_fmac_f32_e32 v54, 0x3377d1cf, v53
	v_fmac_f32_e32 v54, 0x3f317217, v53
	v_cmp_lt_f32_e64 s[38:39], |v53|, s58
	s_nop 1
	v_cndmask_b32_e64 v53, v53, v54, s[38:39]
	v_cndmask_b32_e32 v54, 0, v229, vcc
	v_sub_f32_e32 v53, v53, v54
	v_sub_f32_e32 v90, v52, v53
	ds_read_b128 v[52:55], v72 offset:65088
	s_waitcnt lgkmcnt(0)
	v_fma_f32 v56, v51, v52, v88
	v_fmac_f32_e32 v56, v65, v53
	v_fmac_f32_e32 v56, v67, v54
	v_fmac_f32_e32 v56, v71, v55
	ds_read_b128 v[52:55], v72 offset:65104
	s_waitcnt lgkmcnt(0)
	v_fmac_f32_e32 v56, v76, v52
	v_fmac_f32_e32 v56, v77, v53
	v_fmac_f32_e32 v56, v78, v54
	v_fmac_f32_e32 v56, v79, v55
	ds_read_b128 v[52:55], v72 offset:65120
	s_waitcnt lgkmcnt(0)
; __device__ __forceinline__ void gla_decay(unsigned char* lds, const float* glow_t0, const float* Wg  , const float* bg  , int dir) {
;     ...
;     for (int k = 0; k < 8; ++k) { const float* gl = GLs + (seg * 8 + k) * 16; float a = bias;
; #pragma unroll
;         for (int r = 0; r < 16; ++r) a += gl[r] * w[r];
;         loc[k] = (fminf(a, 0.f) - __logf(1.f + __expf(-fabsf(a)))) * (1.f / 16.f); }
	v_fmac_f32_e32 v56, v80, v52
	v_fmac_f32_e32 v56, v81, v53
	v_fmac_f32_e32 v56, v82, v54
	v_fmac_f32_e32 v56, v83, v55
	ds_read_b128 v[52:55], v72 offset:65136
	s_waitcnt lgkmcnt(0)
	v_fmac_f32_e32 v56, v84, v52
	v_fmac_f32_e32 v56, v85, v53
	v_fmac_f32_e32 v56, v86, v54
	v_fmac_f32_e32 v56, v87, v55
	v_mul_f32_e64 v53, |v56|, s55
	v_exp_f32_e32 v53, v53
	v_min_f32_e32 v52, 0, v56
	v_add_f32_e32 v53, 1.0, v53
	v_cmp_gt_f32_e32 vcc, s33, v53
	s_nop 1
	v_cndmask_b32_e64 v54, 0, 32, vcc
	v_ldexp_f32 v53, v53, v54
	v_log_f32_e32 v53, v53
	s_nop 0
	v_mul_f32_e32 v54, 0x3f317217, v53
	v_fma_f32 v54, v53, s57, -v54
	v_fmac_f32_e32 v54, 0x3377d1cf, v53
	v_fmac_f32_e32 v54, 0x3f317217, v53
	v_cmp_lt_f32_e64 s[38:39], |v53|, s58
	s_nop 1
	v_cndmask_b32_e64 v53, v53, v54, s[38:39]
	v_cndmask_b32_e32 v54, 0, v229, vcc
	v_sub_f32_e32 v53, v53, v54
	v_sub_f32_e32 v91, v52, v53
	ds_read_b128 v[52:55], v72 offset:65024
	s_waitcnt lgkmcnt(0)
	v_fma_f32 v56, v51, v52, v88
	v_fmac_f32_e32 v56, v65, v53
	v_fmac_f32_e32 v56, v67, v54
	v_fmac_f32_e32 v56, v71, v55
	ds_read_b128 v[52:55], v72 offset:65040
	s_waitcnt lgkmcnt(0)
	v_fmac_f32_e32 v56, v76, v52
	v_fmac_f32_e32 v56, v77, v53
	v_fmac_f32_e32 v56, v78, v54
	v_fmac_f32_e32 v56, v79, v55
	ds_read_b128 v[52:55], v72 offset:65056
	s_waitcnt lgkmcnt(0)
	v_fmac_f32_e32 v56, v80, v52
	v_fmac_f32_e32 v56, v81, v53
	v_fmac_f32_e32 v56, v82, v54
	v_fmac_f32_e32 v56, v83, v55
	ds_read_b128 v[52:55], v72 offset:65072
	s_waitcnt lgkmcnt(0)
	v_fmac_f32_e32 v56, v84, v52
	v_fmac_f32_e32 v56, v85, v53
	v_fmac_f32_e32 v56, v86, v54
	v_fmac_f32_e32 v56, v87, v55
	v_mul_f32_e64 v53, |v56|, s55
	v_exp_f32_e32 v53, v53
	v_min_f32_e32 v52, 0, v56
	v_add_f32_e32 v53, 1.0, v53
	v_cmp_gt_f32_e32 vcc, s33, v53
	s_nop 1
	v_cndmask_b32_e64 v54, 0, 32, vcc
	v_ldexp_f32 v53, v53, v54
	v_log_f32_e32 v53, v53
	s_nop 0
	v_mul_f32_e32 v54, 0x3f317217, v53
	v_fma_f32 v54, v53, s57, -v54
	v_fmac_f32_e32 v54, 0x3377d1cf, v53
	v_fmac_f32_e32 v54, 0x3f317217, v53
	v_cmp_lt_f32_e64 s[38:39], |v53|, s58
	s_nop 1
	v_cndmask_b32_e64 v53, v53, v54, s[38:39]
	v_cndmask_b32_e32 v54, 0, v229, vcc
	v_sub_f32_e32 v53, v53, v54
	v_sub_f32_e32 v92, v52, v53
	ds_read_b128 v[52:55], v72 offset:64960
	s_waitcnt lgkmcnt(0)
	v_fma_f32 v56, v51, v52, v88
	v_fmac_f32_e32 v56, v65, v53
	v_fmac_f32_e32 v56, v67, v54
	v_fmac_f32_e32 v56, v71, v55
	ds_read_b128 v[52:55], v72 offset:64976
	s_waitcnt lgkmcnt(0)
	v_fmac_f32_e32 v56, v76, v52
	v_fmac_f32_e32 v56, v77, v53
	v_fmac_f32_e32 v56, v78, v54
	v_fmac_f32_e32 v56, v79, v55
	ds_read_b128 v[52:55], v72 offset:64992
	s_waitcnt lgkmcnt(0)
	v_fmac_f32_e32 v56, v80, v52
	v_fmac_f32_e32 v56, v81, v53
	v_fmac_f32_e32 v56, v82, v54
	v_fmac_f32_e32 v56, v83, v55
	ds_read_b128 v[52:55], v72 offset:65008
	s_waitcnt lgkmcnt(0)
	v_fmac_f32_e32 v56, v84, v52
	v_fmac_f32_e32 v56, v85, v53
	v_fmac_f32_e32 v56, v86, v54
	v_fmac_f32_e32 v56, v87, v55
	v_mul_f32_e64 v53, |v56|, s55
	v_exp_f32_e32 v53, v53
	v_min_f32_e32 v52, 0, v56
	v_add_f32_e32 v53, 1.0, v53
	v_cmp_gt_f32_e32 vcc, s33, v53
	s_nop 1
	v_cndmask_b32_e64 v54, 0, 32, vcc
	v_ldexp_f32 v53, v53, v54
	v_log_f32_e32 v53, v53
	s_nop 0
	v_mul_f32_e32 v54, 0x3f317217, v53
	v_fma_f32 v54, v53, s57, -v54
	v_fmac_f32_e32 v54, 0x3377d1cf, v53
	v_fmac_f32_e32 v54, 0x3f317217, v53
	v_cmp_lt_f32_e64 s[38:39], |v53|, s58
	s_nop 1
	v_cndmask_b32_e64 v53, v53, v54, s[38:39]
	v_cndmask_b32_e32 v54, 0, v229, vcc
	v_sub_f32_e32 v53, v53, v54
	v_sub_f32_e32 v93, v52, v53
	ds_read_b128 v[52:55], v72 offset:64896
	s_waitcnt lgkmcnt(0)
	v_fma_f32 v56, v51, v52, v88
	v_fmac_f32_e32 v56, v65, v53
	v_fmac_f32_e32 v56, v67, v54
	v_fmac_f32_e32 v56, v71, v55
	ds_read_b128 v[52:55], v72 offset:64912
	s_waitcnt lgkmcnt(0)
	v_fmac_f32_e32 v56, v76, v52
	v_fmac_f32_e32 v56, v77, v53
	v_fmac_f32_e32 v56, v78, v54
	v_fmac_f32_e32 v56, v79, v55
	ds_read_b128 v[52:55], v72 offset:64928
	s_waitcnt lgkmcnt(0)
	v_fmac_f32_e32 v56, v80, v52
	v_fmac_f32_e32 v56, v81, v53
	v_fmac_f32_e32 v56, v82, v54
	v_fmac_f32_e32 v56, v83, v55
	ds_read_b128 v[52:55], v72 offset:64944
	s_waitcnt lgkmcnt(0)
	v_fmac_f32_e32 v56, v84, v52
	v_fmac_f32_e32 v56, v85, v53
	v_fmac_f32_e32 v56, v86, v54
	v_fmac_f32_e32 v56, v87, v55
	v_mul_f32_e64 v53, |v56|, s55
	v_exp_f32_e32 v53, v53
	v_min_f32_e32 v52, 0, v56
	v_add_f32_e32 v53, 1.0, v53
	v_cmp_gt_f32_e32 vcc, s33, v53
	s_nop 1
	v_cndmask_b32_e64 v54, 0, 32, vcc
	v_ldexp_f32 v53, v53, v54
	v_log_f32_e32 v53, v53
	s_nop 0
	v_mul_f32_e32 v54, 0x3f317217, v53
	v_fma_f32 v54, v53, s57, -v54
	v_fmac_f32_e32 v54, 0x3377d1cf, v53
	v_fmac_f32_e32 v54, 0x3f317217, v53
	v_cmp_lt_f32_e64 s[38:39], |v53|, s58
	s_nop 1
	v_cndmask_b32_e64 v53, v53, v54, s[38:39]
	v_cndmask_b32_e32 v54, 0, v229, vcc
	v_sub_f32_e32 v53, v53, v54
	v_sub_f32_e32 v94, v52, v53
	ds_read_b128 v[52:55], v72 offset:64832
	s_waitcnt lgkmcnt(0)
	v_fma_f32 v56, v51, v52, v88
	v_fmac_f32_e32 v56, v65, v53
	v_fmac_f32_e32 v56, v67, v54
	v_fmac_f32_e32 v56, v71, v55
	ds_read_b128 v[52:55], v72 offset:64848
	s_waitcnt lgkmcnt(0)
	v_fmac_f32_e32 v56, v76, v52
	v_fmac_f32_e32 v56, v77, v53
	v_fmac_f32_e32 v56, v78, v54
	v_fmac_f32_e32 v56, v79, v55
	ds_read_b128 v[52:55], v72 offset:64864
	s_waitcnt lgkmcnt(0)
	v_fmac_f32_e32 v56, v80, v52
	v_fmac_f32_e32 v56, v81, v53
	v_fmac_f32_e32 v56, v82, v54
	v_fmac_f32_e32 v56, v83, v55
	ds_read_b128 v[52:55], v72 offset:64880
	s_waitcnt lgkmcnt(0)
; __device__ __forceinline__ u32x4 pack8(const float* v) { u32x4 w; w.x = pk2(v[0], v[1]); w.y = pk2(v[2], v[3]); w.z = pk2(v[4], v[5]); w.w = pk2(v[6], v[7]); return w; }
; __device__ __forceinline__ void unpack8(u32x4 w, float* v) { v[0] = bflo(w.x); v[1] = bfhi(w.x); v[2] = bflo(w.y); v[3] = bfhi(w.y); v[4] = bflo(w.z); v[5] = bfhi(w.z); v[6] = bflo(w.w); v[7] = bfhi(w.w); }
; __device__ __forceinline__ void gla_decay(unsigned char* lds, const float* glow_t0, const float* Wg  , const float* bg  , int dir) {
;     ...
;     for (int k = 0; k < 8; ++k) { const float* gl = GLs + (seg * 8 + k) * 16; float a = bias;
; #pragma unroll
;         for (int r = 0; r < 16; ++r) a += gl[r] * w[r];
;         loc[k] = (fminf(a, 0.f) - __logf(1.f + __expf(-fabsf(a)))) * (1.f / 16.f); }
;     float run = 0.f;
;     if (dir == 0) {
; #pragma unroll
;         for (int k = 0; k < 8; ++k) { run += loc[k]; loc[k] = run; }
;     } else {
; #pragma unroll
;         for (int k = 7; k >= 0; --k) { run += loc[k]; loc[k] = run; }
;     }
;     Tot[seg * 64 + d] = run;
;     __syncthreads();
;     float off = 0.f;
; #pragma unroll
;     for (int sg = 0; sg < 8; ++sg) { const float tv = Tot[sg * 64 + d]; if (dir == 0 ? (sg < seg) : (sg > seg)) off += tv; }
; #pragma unroll
;     for (int k = 0; k < 8; ++k) Bs[(seg * 8 + k) * 65 + d] = loc[k] + off;
;     __syncthreads();
; __device__ __forceinline__ void gla_out_item(unsigned char* lds, unsigned char* ws, const float* wgate, const float* bgate, const float* hnorm, int l, int item, bool dowrite = true) {
;     ...
;         { const int s = tid >> 3, dg = tid & 7;
;           float qv[8], kv[8];
;           unpack8(qraw, qv);
;           unpack8(kraw, kv);
; #pragma unroll
;           for (int e = 0; e < 8; ++e) { const float bv = Bs[s * 65 + dg * 8 + e]; qv[e] *= __expf(bv); kv[e] *= __expf(-bv); }
;           *(u32x4*)(QE + s * 72 + dg * 8) = pack8(qv); *(u32x4*)(KE + s * 72 + dg * 8) = pack8(kv); }
;         __syncthreads();
	v_fmac_f32_e32 v56, v84, v52
	v_fmac_f32_e32 v56, v85, v53
	v_fmac_f32_e32 v56, v86, v54
	v_fmac_f32_e32 v56, v87, v55
	v_mul_f32_e64 v53, |v56|, s55
	v_exp_f32_e32 v53, v53
	v_min_f32_e32 v52, 0, v56
	v_add_f32_e32 v53, 1.0, v53
	v_cmp_gt_f32_e32 vcc, s33, v53
	s_nop 1
	v_cndmask_b32_e64 v54, 0, 32, vcc
	v_ldexp_f32 v53, v53, v54
	v_log_f32_e32 v53, v53
	s_nop 0
	v_mul_f32_e32 v54, 0x3f317217, v53
	v_fma_f32 v54, v53, s57, -v54
	v_fmac_f32_e32 v54, 0x3377d1cf, v53
	v_fmac_f32_e32 v54, 0x3f317217, v53
	v_cmp_lt_f32_e64 s[38:39], |v53|, s58
	s_nop 1
	v_cndmask_b32_e64 v53, v53, v54, s[38:39]
	v_cndmask_b32_e32 v54, 0, v229, vcc
	v_sub_f32_e32 v53, v53, v54
	v_sub_f32_e32 v95, v52, v53
	ds_read_b128 v[52:55], v72 offset:64768
	ds_read_b128 v[56:59], v72 offset:64784
	ds_read_b128 v[60:63], v72 offset:64800
	ds_read_b128 v[72:75], v72 offset:64816
	s_waitcnt lgkmcnt(3)
	v_fmac_f32_e32 v88, v51, v52
	v_fmac_f32_e32 v88, v65, v53
	v_fmac_f32_e32 v88, v67, v54
	v_fmac_f32_e32 v88, v71, v55
	s_waitcnt lgkmcnt(2)
	v_fmac_f32_e32 v88, v76, v56
	v_fmac_f32_e32 v88, v77, v57
	v_fmac_f32_e32 v88, v78, v58
	v_fmac_f32_e32 v88, v79, v59
	s_waitcnt lgkmcnt(1)
	v_fmac_f32_e32 v88, v80, v60
	v_fmac_f32_e32 v88, v81, v61
	v_fmac_f32_e32 v88, v82, v62
	v_fmac_f32_e32 v88, v83, v63
	s_waitcnt lgkmcnt(0)
	v_fmac_f32_e32 v88, v84, v72
	v_fmac_f32_e32 v88, v85, v73
	v_fmac_f32_e32 v88, v86, v74
	v_fmac_f32_e32 v88, v87, v75
	v_mul_f32_e64 v52, |v88|, s55
	v_exp_f32_e32 v52, v52
	v_min_f32_e32 v51, 0, v88
	v_lshlrev_b32_e32 v62, 16, v27
	v_and_b32_e32 v63, 0xffff0000, v27
	v_add_f32_e32 v52, 1.0, v52
	v_cmp_gt_f32_e32 vcc, s33, v52
	v_and_or_b32 v71, v43, 32, v69
	s_nop 0
	v_cndmask_b32_e64 v53, 0, 32, vcc
	v_ldexp_f32 v52, v52, v53
	v_log_f32_e32 v52, v52
	s_nop 0
	v_mul_f32_e32 v53, 0x3f317217, v52
	v_fma_f32 v53, v52, s57, -v53
	v_fmac_f32_e32 v53, 0x3377d1cf, v52
	v_fmac_f32_e32 v53, 0x3f317217, v52
	v_cmp_lt_f32_e64 s[38:39], |v52|, s58
	s_nop 1
	v_cndmask_b32_e64 v52, v52, v53, s[38:39]
	v_cndmask_b32_e32 v53, 0, v229, vcc
	v_sub_f32_e32 v52, v52, v53
	v_sub_f32_e32 v51, v51, v52
	v_fma_f32 v51, v51, s62, 0
	v_fmamk_f32 v54, v95, 0x3d800000, v51
	v_fmamk_f32 v55, v94, 0x3d800000, v54
	v_fmamk_f32 v56, v93, 0x3d800000, v55
	v_fmamk_f32 v57, v92, 0x3d800000, v56
	v_fmamk_f32 v58, v91, 0x3d800000, v57
	v_fmamk_f32 v59, v90, 0x3d800000, v58
	v_fmamk_f32 v60, v89, 0x3d800000, v59
	v_add_u32_e32 v52, 0, v64
	ds_write_b32 v52, v60 offset:16640
	s_waitcnt lgkmcnt(0)
	s_barrier
	ds_read2st64_b32 v[52:53], v50 offset0:65 offset1:66
	v_cmp_lt_i32_e32 vcc, 0, v49
	s_waitcnt lgkmcnt(0)
	v_add_f32_e32 v52, 0, v52
	v_cndmask_b32_e32 v52, 0, v52, vcc
	v_cmp_lt_i32_e32 vcc, 1, v49
	v_add_f32_e32 v53, v53, v52
	s_nop 0
	v_cndmask_b32_e32 v61, v52, v53, vcc
	ds_read2st64_b32 v[52:53], v50 offset0:67 offset1:68
	v_cmp_lt_i32_e32 vcc, 2, v49
	s_waitcnt lgkmcnt(0)
	v_add_f32_e32 v52, v52, v61
	v_cndmask_b32_e32 v52, v61, v52, vcc
	v_cmp_lt_i32_e32 vcc, 3, v49
	v_add_f32_e32 v53, v53, v52
	s_nop 0
	v_cndmask_b32_e32 v61, v52, v53, vcc
	ds_read2st64_b32 v[52:53], v50 offset0:69 offset1:70
	v_cmp_lt_i32_e32 vcc, 4, v49
	s_waitcnt lgkmcnt(0)
	v_add_f32_e32 v52, v52, v61
	v_cndmask_b32_e32 v52, v61, v52, vcc
	v_cmp_lt_i32_e32 vcc, 5, v49
	v_add_f32_e32 v53, v53, v52
	s_nop 0
	v_cndmask_b32_e32 v61, v52, v53, vcc
	ds_read2st64_b32 v[52:53], v50 offset0:71 offset1:72
	v_cmp_lt_i32_e32 vcc, 6, v49
	s_waitcnt lgkmcnt(0)
	v_add_f32_e32 v52, v52, v61
	v_cndmask_b32_e32 v52, v61, v52, vcc
	v_cmp_lt_i32_e32 vcc, 7, v49
	v_add_f32_e32 v53, v53, v52
	s_nop 0
	v_cndmask_b32_e32 v52, v52, v53, vcc
	v_add_f32_e32 v53, v51, v52
	v_mad_u64_u32 v[50:51], s[0:1], v49, s59, v[50:51]
	v_add_f32_e32 v49, v54, v52
	ds_write2_b32 v50, v53, v49 offset1:65
	v_add_f32_e32 v49, v55, v52
	v_add_f32_e32 v51, v56, v52
	ds_write2_b32 v50, v49, v51 offset0:130 offset1:195
	v_add_f32_e32 v49, v57, v52
	v_add_f32_e32 v51, v58, v52
	v_add_u32_e32 v50, 0x400, v50
	ds_write2_b32 v50, v49, v51 offset0:4 offset1:69
	v_add_f32_e32 v49, v59, v52
	v_add_f32_e32 v51, v60, v52
	ds_write2_b32 v50, v49, v51 offset0:134 offset1:199
	s_waitcnt lgkmcnt(0)
	s_barrier
	ds_read2_b32 v[52:53], v48 offset1:1
	v_lshlrev_b32_e32 v50, 16, v24
	v_and_b32_e32 v51, 0xffff0000, v24
	v_cmp_gt_i32_e32 vcc, v71, v39
	s_waitcnt lgkmcnt(0)
	v_mul_f32_e32 v49, 0x3fb8aa3b, v52
	v_exp_f32_e32 v54, v49
	v_mul_f32_e32 v49, 0xbfb8aa3b, v52
	v_mul_f32_e32 v24, 0xbfb8aa3b, v53
	v_exp_f32_e32 v56, v49
	v_exp_f32_e32 v57, v24
	v_mul_f32_e32 v49, 0x3fb8aa3b, v53
	v_lshlrev_b32_e32 v52, 16, v20
	v_and_b32_e32 v53, 0xffff0000, v20
	v_pk_mul_f32 v[74:75], v[56:57], v[52:53]
	ds_read2_b32 v[56:57], v48 offset0:2 offset1:3
	v_exp_f32_e32 v55, v49
	s_waitcnt lgkmcnt(0)
	v_mul_f32_e32 v20, 0x3fb8aa3b, v56
	v_exp_f32_e32 v58, v20
	v_mul_f32_e32 v20, 0xbfb8aa3b, v56
	v_exp_f32_e32 v24, v20
	v_mul_f32_e32 v20, 0x3fb8aa3b, v57
	v_exp_f32_e32 v59, v20
	v_mul_f32_e32 v20, 0xbfb8aa3b, v57
	v_pk_mul_f32 v[72:73], v[54:55], v[50:51]
	v_lshlrev_b32_e32 v54, 16, v25
	v_and_b32_e32 v55, 0xffff0000, v25
	v_exp_f32_e32 v25, v20
	v_lshlrev_b32_e32 v56, 16, v21
	v_and_b32_e32 v57, 0xffff0000, v21
	ds_read2_b32 v[20:21], v48 offset0:4 offset1:5
	v_pk_mul_f32 v[76:77], v[58:59], v[54:55]
	v_lshlrev_b32_e32 v58, 16, v26
	v_and_b32_e32 v59, 0xffff0000, v26
	v_pk_mul_f32 v[24:25], v[24:25], v[56:57]
	s_waitcnt lgkmcnt(0)
	v_mul_f32_e32 v49, 0x3fb8aa3b, v20
	v_exp_f32_e32 v60, v49
	v_mul_f32_e32 v49, 0x3fb8aa3b, v21
	v_mul_f32_e32 v20, 0xbfb8aa3b, v20
	v_exp_f32_e32 v61, v49
	v_mul_f32_e32 v21, 0xbfb8aa3b, v21
	v_exp_f32_e32 v20, v20
	v_exp_f32_e32 v21, v21
	v_pk_mul_f32 v[78:79], v[60:61], v[58:59]
	v_lshlrev_b32_e32 v60, 16, v22
	v_and_b32_e32 v61, 0xffff0000, v22
	v_pk_mul_f32 v[80:81], v[20:21], v[60:61]
	ds_read2_b32 v[20:21], v48 offset0:6 offset1:7
	v_mad_u32_u24 v49, v71, s76, v66
	v_or_b32_e32 v66, 1, v39
	v_cmp_le_i32_e64 s[38:39], v71, v66
	s_waitcnt lgkmcnt(0)
	v_mul_f32_e32 v22, 0x3fb8aa3b, v20
	v_exp_f32_e32 v64, v22
	v_mul_f32_e32 v22, 0x3fb8aa3b, v21
	v_mul_f32_e32 v20, 0xbfb8aa3b, v20
	v_exp_f32_e32 v65, v22
	v_mul_f32_e32 v21, 0xbfb8aa3b, v21
	v_exp_f32_e32 v20, v20
	v_exp_f32_e32 v21, v21
	v_pk_mul_f32 v[26:27], v[64:65], v[62:63]
	v_lshlrev_b32_e32 v64, 16, v23
	v_and_b32_e32 v65, 0xffff0000, v23
	v_pk_mul_f32 v[82:83], v[20:21], v[64:65]
	v_cvt_pk_bf16_f32 v20, v72, v73
	v_cvt_pk_bf16_f32 v21, v76, v77
	v_cvt_pk_bf16_f32 v22, v78, v79
	v_cvt_pk_bf16_f32 v23, v26, v27
	ds_write_b128 v42, v[20:23] offset:18688
	v_cvt_pk_bf16_f32 v20, v74, v75
	v_cvt_pk_bf16_f32 v21, v24, v25
	v_cvt_pk_bf16_f32 v22, v80, v81
	v_cvt_pk_bf16_f32 v23, v82, v83
	ds_write_b128 v42, v[20:23] offset:27904
	s_waitcnt lgkmcnt(0)
	s_barrier
; __device__ __forceinline__ void gla_decay(unsigned char* lds, const float* glow_t0, const float* Wg  , const float* bg  , int dir) {
;     ...
;     { const int s = tid >> 3, q = tid & 7;
;       const float* gp = glow_t0 + (size_t)s * 32 + dir * 16 + q * 2;
;       GLs[s * 16 + q * 2] = gp[0]; GLs[s * 16 + q * 2 + 1] = gp[1]; }
;     const int d = tid & 63, seg = tid >> 6;
;     float w[16];
; #pragma unroll
;     for (int r = 0; r < 16; ++r) w[r] = Wg[r * 256 + d];
;     const float bias = bg[d];
;     __syncthreads();
; __device__ __forceinline__ void gla_out_item(unsigned char* lds, unsigned char* ws, const float* wgate, const float* bgate, const float* hnorm, int l, int item, bool dowrite = true) {
;     ...
;         { const int rb = wid >> 1;
; #pragma unroll
;           for (int cc = 0; cc < 2; ++cc) { const int cb = (wid & 1) * 2 + cc; f32x4 a4 = (f32x4){0.f, 0.f, 0.f, 0.f};
; #pragma unroll
;               for (int kk = 0; kk < 2; ++kk) { const bf16x8 a = *(const bf16x8*)(QE + (rb * 16 + ql) * 72 + kk * 32 + g * 8); const bf16x8 bb = *(const bf16x8*)(KE + (cb * 16 + ql) * 72 + kk * 32 + g * 8);
;                   a4 = __builtin_amdgcn_mfma_f32_16x16x32_bf16(a, bb, a4, 0, 0, 0); }
; #pragma unroll
;               for (int j = 0; j < 4; ++j) { const int i = rb * 16 + g * 4 + j, ip = cb * 16 + ql; const bool keep = dir == 0 ? (ip <= i) : (ip >= i); ATT[i * 72 + ip] = (bf16_t)f2bf(keep ? a4[j] : 0.f); } } }
;         __syncthreads();
;         { const int sidx = ((b * 4 + h) * 2 + dir) * 132 + c;
;           const bf16_t* st = (const bf16_t*)(ws + O_ST) + (size_t)sidx * 8192;
; #pragma unroll
;           for (int kk = 0; kk < 2; ++kk) {
;               const bf16x8 bv = *(const bf16x8*)(Vt + (wid * 16 + ql) * 72 + kk * 32 + g * 8);
;               const bf16x8 bs = dir == 0 ? sfr[0][kk] : sfr[1][kk];
; #pragma unroll
;               for (int rb = 0; rb < 4; ++rb) {
;                   const bf16x8 a1 = *(const bf16x8*)(ATT + (rb * 16 + ql) * 72 + kk * 32 + g * 8);
;                   const bf16x8 a2 = *(const bf16x8*)(QE + (rb * 16 + ql) * 72 + kk * 32 + g * 8);
;                   oacc[rb] = __builtin_amdgcn_mfma_f32_16x16x32_bf16(a1, bv, oacc[rb], 0, 0, 0);
;                   oacc[rb] = __builtin_amdgcn_mfma_f32_16x16x32_bf16(a2, bs, oacc[rb], 0, 0, 0);
;               } } }
	ds_read_b128 v[20:23], v38 offset:18688
	ds_read_b128 v[24:27], v49 offset:27904
	s_waitcnt lgkmcnt(0)
	v_mfma_f32_16x16x32_bf16 v[20:23], v[20:23], v[24:27], 0
	ds_read_b128 v[24:27], v38 offset:18752
	ds_read_b128 v[72:75], v49 offset:27968
	s_waitcnt lgkmcnt(0)
	v_mfma_f32_16x16x32_bf16 v[20:23], v[24:27], v[72:75], v[20:23]
	v_lshlrev_b32_e32 v24, 1, v71
	v_or_b32_e32 v72, 2, v39
	v_or_b32_e32 v73, 3, v39
	s_nop 4
	v_cndmask_b32_e64 v20, v20, 0, vcc
	v_bfe_u32 v25, v20, 16, 1
	v_add3_u32 v20, v20, v25, s86
	v_mul_lo_u32 v25, v39, s76
	v_add3_u32 v43, 0, v24, v25
	ds_write_b16_d16_hi v43, v20 offset:37120
	v_cndmask_b32_e64 v20, 0, v21, s[38:39]
	v_bfe_u32 v21, v20, 16, 1
	v_add3_u32 v20, v20, v21, s86
	v_cmp_le_i32_e64 s[38:39], v71, v72
	ds_write_b16_d16_hi v43, v20 offset:37264
	v_or_b32_e32 v74, 16, v71
	v_cndmask_b32_e64 v20, 0, v22, s[38:39]
	v_bfe_u32 v21, v20, 16, 1
	v_add3_u32 v20, v20, v21, s86
	v_cmp_le_i32_e64 s[38:39], v71, v73
	ds_write_b16_d16_hi v43, v20 offset:37408
	v_cmp_le_i32_e64 s[40:41], v74, v66
	v_cndmask_b32_e64 v20, 0, v23, s[38:39]
	v_bfe_u32 v21, v20, 16, 1
	v_add3_u32 v20, v20, v21, s86
	ds_write_b16_d16_hi v43, v20 offset:37552
	ds_read_b128 v[20:23], v38 offset:18688
	ds_read_b128 v[24:27], v49 offset:30208
	s_waitcnt lgkmcnt(0)
	v_mfma_f32_16x16x32_bf16 v[20:23], v[20:23], v[24:27], 0
	ds_read_b128 v[24:27], v38 offset:18752
	ds_read_b128 v[76:79], v49 offset:30272
	v_cmp_gt_i32_e64 s[38:39], v74, v39
	v_mov_b32_e32 v75, v203
	s_waitcnt lgkmcnt(0)
	v_mfma_f32_16x16x32_bf16 v[20:23], v[24:27], v[76:79], v[20:23]
	s_nop 7
	v_cndmask_b32_e64 v20, v20, 0, s[38:39]
	v_bfe_u32 v24, v20, 16, 1
	v_add3_u32 v20, v20, v24, s86
	ds_write_b16_d16_hi v43, v20 offset:37152
	v_cndmask_b32_e64 v20, 0, v21, s[40:41]
	v_bfe_u32 v21, v20, 16, 1
	v_add3_u32 v20, v20, v21, s86
	v_cmp_le_i32_e64 s[40:41], v74, v72
	ds_write_b16_d16_hi v43, v20 offset:37296
	s_nop 0
	v_cndmask_b32_e64 v20, 0, v22, s[40:41]
	v_bfe_u32 v21, v20, 16, 1
	v_add3_u32 v20, v20, v21, s86
	v_cmp_le_i32_e64 s[40:41], v74, v73
	ds_write_b16_d16_hi v43, v20 offset:37440
	s_nop 0
	v_cndmask_b32_e64 v20, 0, v23, s[40:41]
	v_bfe_u32 v21, v20, 16, 1
	v_add3_u32 v20, v20, v21, s86
	ds_write_b16_d16_hi v43, v20 offset:37584
	s_waitcnt lgkmcnt(0)
	s_barrier
	ds_read_b128 v[20:23], v34 offset:46336
	ds_read_b128 v[24:27], v35 offset:37120
	ds_read_b128 v[76:79], v35 offset:18688
	s_waitcnt lgkmcnt(1)
	v_mfma_f32_16x16x32_bf16 v[24:27], v[24:27], v[20:23], 0
	s_add_u32 s40, s48, s28
	s_addc_u32 s41, s49, s29
	s_add_u32 s48, s53, s34
	s_waitcnt lgkmcnt(0)
	v_mfma_f32_16x16x32_bf16 v[24:27], v[76:79], v[16:19], v[24:27]
	ds_read_b128 v[76:79], v35 offset:39424
	ds_read_b128 v[80:83], v35 offset:20992
	s_addc_u32 s49, s54, s35
	s_waitcnt lgkmcnt(1)
	v_mfma_f32_16x16x32_bf16 v[76:79], v[76:79], v[20:23], 0
	s_waitcnt lgkmcnt(0)
	v_mfma_f32_16x16x32_bf16 v[76:79], v[80:83], v[16:19], v[76:79]
	ds_read_b128 v[80:83], v35 offset:41728
	ds_read_b128 v[84:87], v35 offset:23296
	s_waitcnt lgkmcnt(1)
	v_mfma_f32_16x16x32_bf16 v[80:83], v[80:83], v[20:23], 0
	s_waitcnt lgkmcnt(0)
	v_mfma_f32_16x16x32_bf16 v[80:83], v[84:87], v[16:19], v[80:83]
	ds_read_b128 v[84:87], v35 offset:44032
	ds_read_b128 v[88:91], v35 offset:25600
	s_waitcnt lgkmcnt(1)
	v_mfma_f32_16x16x32_bf16 v[20:23], v[84:87], v[20:23], 0
	s_waitcnt lgkmcnt(0)
	v_mfma_f32_16x16x32_bf16 v[84:87], v[88:91], v[16:19], v[20:23]
	ds_read_b128 v[88:91], v34 offset:46400
	ds_read_b128 v[16:19], v35 offset:37184
	s_nop 3
	ds_read_b128 v[20:23], v35 offset:18752
	s_waitcnt lgkmcnt(1)
	v_mfma_f32_16x16x32_bf16 v[16:19], v[16:19], v[88:91], v[24:27]
	s_waitcnt lgkmcnt(0)
	v_mfma_f32_16x16x32_bf16 v[16:19], v[20:23], v[28:31], v[16:19]
	ds_read_b128 v[20:23], v35 offset:39488
	ds_read_b128 v[24:27], v35 offset:21056
	s_waitcnt lgkmcnt(1)
	v_mfma_f32_16x16x32_bf16 v[20:23], v[20:23], v[88:91], v[76:79]
	s_waitcnt lgkmcnt(0)
	v_mfma_f32_16x16x32_bf16 v[20:23], v[24:27], v[28:31], v[20:23]
	ds_read_b128 v[24:27], v35 offset:41792
	ds_read_b128 v[76:79], v35 offset:23360
	s_waitcnt lgkmcnt(1)
	v_mfma_f32_16x16x32_bf16 v[24:27], v[24:27], v[88:91], v[80:83]
	s_waitcnt lgkmcnt(0)
	v_mfma_f32_16x16x32_bf16 v[24:27], v[76:79], v[28:31], v[24:27]
	ds_read_b128 v[76:79], v35 offset:44096
	ds_read_b128 v[80:83], v35 offset:25664
	s_waitcnt lgkmcnt(0)
	s_barrier
	v_mfma_f32_16x16x32_bf16 v[76:79], v[76:79], v[88:91], v[84:87]
	s_nop 0
	v_ashrrev_i32_e32 v66, 3, v75
	v_ashrrev_i32_e32 v67, 31, v66
	v_mfma_f32_16x16x32_bf16 v[28:31], v[80:83], v[28:31], v[76:79]
	v_lshlrev_b32_e32 v92, 2, v75
	s_nop 2
	v_lshlrev_b64 v[76:77], 7, v[66:67]
	v_lshlrev_b32_e32 v67, 3, v75
	v_lshl_add_u64 v[76:77], s[42:43], 0, v[76:77]
	v_and_b32_e32 v78, 56, v67
	v_mov_b32_e32 v79, v36
	v_lshl_add_u64 v[76:77], v[76:77], 0, v[78:79]
	v_lshlrev_b32_e32 v66, 6, v66
	v_add3_u32 v78, 0, v66, v78
	v_ashrrev_i32_e32 v75, 6, v75
	v_lshl_add_u32 v88, v75, 9, 0
	s_waitcnt vmcnt(0)
	ds_write_b64 v78, v[132:133] offset:64768
	v_and_b32_e32 v66, 0xfc, v92
	v_mov_b32_e32 v67, v36
	v_lshl_add_u64 v[76:77], s[40:41], 0, v[66:67]
	v_add_co_u32_e64 v78, s[40:41], s69, v76
	s_nop 1
	v_addc_co_u32_e64 v79, s[40:41], 0, v77, s[40:41]
	v_add_co_u32_e64 v80, s[40:41], s67, v76
	s_nop 1
	v_addc_co_u32_e64 v81, s[40:41], 0, v77, s[40:41]
	v_add_co_u32_e64 v76, s[40:41], s66, v76
	v_addc_co_u32_e64 v77, s[40:41], 0, v77, s[40:41]
	s_waitcnt lgkmcnt(0)
	s_barrier
; __device__ __forceinline__ void gla_decay(unsigned char* lds, const float* glow_t0, const float* Wg  , const float* bg  , int dir) {
;     ...
;     for (int r = 0; r < 16; ++r) w[r] = Wg[r * 256 + d];
;     const float bias = bg[d];
;     __syncthreads();
;     float loc[8];
; #pragma unroll
;     for (int k = 0; k < 8; ++k) { const float* gl = GLs + (seg * 8 + k) * 16; float a = bias;
; #pragma unroll
;         for (int r = 0; r < 16; ++r) a += gl[r] * w[r];
;         loc[k] = (fminf(a, 0.f) - __logf(1.f + __expf(-fabsf(a)))) * (1.f / 16.f); }
	ds_read_b128 v[76:79], v88 offset:65216
	v_add_u32_e32 v66, 0, v66
	s_waitcnt vmcnt(0) lgkmcnt(0)
	v_mov_b32_e32 v67, v159
	v_mov_b32_e32 v93, v160
	v_mov_b32_e32 v94, v161
	v_mov_b32_e32 v95, v162
	v_mov_b32_e32 v96, v163
	v_mov_b32_e32 v97, v164
	v_mov_b32_e32 v98, v165
	v_mov_b32_e32 v99, v166
	v_mov_b32_e32 v100, v167
	v_mov_b32_e32 v101, v168
	v_mov_b32_e32 v102, v169
	v_mov_b32_e32 v103, v170
	v_mov_b32_e32 v104, v171
	v_mov_b32_e32 v105, v172
	v_mov_b32_e32 v106, v173
	v_mov_b32_e32 v107, v174
	v_mov_b32_e32 v108, v175
	v_fma_f32 v80, v67, v76, v108
	v_fmac_f32_e32 v80, v93, v77
	v_fmac_f32_e32 v80, v94, v78
	v_fmac_f32_e32 v80, v95, v79
	ds_read_b128 v[76:79], v88 offset:65232
	s_waitcnt lgkmcnt(0)
	v_fmac_f32_e32 v80, v96, v76
	v_fmac_f32_e32 v80, v97, v77
	v_fmac_f32_e32 v80, v98, v78
	v_fmac_f32_e32 v80, v99, v79
	ds_read_b128 v[76:79], v88 offset:65248
	s_waitcnt lgkmcnt(0)
	v_fmac_f32_e32 v80, v100, v76
	v_fmac_f32_e32 v80, v101, v77
	v_fmac_f32_e32 v80, v102, v78
	v_fmac_f32_e32 v80, v103, v79
	ds_read_b128 v[76:79], v88 offset:65264
	s_waitcnt lgkmcnt(0)
	v_fmac_f32_e32 v80, v104, v76
	v_fmac_f32_e32 v80, v105, v77
	v_fmac_f32_e32 v80, v106, v78
	v_fmac_f32_e32 v80, v107, v79
	v_mul_f32_e64 v77, |v80|, s55
	v_exp_f32_e32 v77, v77
	v_min_f32_e32 v76, 0, v80
	v_add_f32_e32 v77, 1.0, v77
	v_cmp_gt_f32_e64 s[40:41], s33, v77
	s_nop 1
	v_cndmask_b32_e64 v78, 0, 32, s[40:41]
	v_ldexp_f32 v77, v77, v78
	v_log_f32_e32 v77, v77
	s_nop 0
	v_mul_f32_e32 v78, 0x3f317217, v77
	v_fma_f32 v78, v77, s57, -v78
	v_fmac_f32_e32 v78, 0x3377d1cf, v77
	v_fmac_f32_e32 v78, 0x3f317217, v77
	v_cmp_lt_f32_e64 s[42:43], |v77|, s58
	s_nop 1
	v_cndmask_b32_e64 v77, v77, v78, s[42:43]
	v_cndmask_b32_e64 v78, 0, v229, s[40:41]
	v_sub_f32_e32 v77, v77, v78
	v_sub_f32_e32 v109, v76, v77
	ds_read_b128 v[76:79], v88 offset:65152
	s_waitcnt lgkmcnt(0)
	v_fma_f32 v80, v67, v76, v108
	v_fmac_f32_e32 v80, v93, v77
	v_fmac_f32_e32 v80, v94, v78
	v_fmac_f32_e32 v80, v95, v79
	ds_read_b128 v[76:79], v88 offset:65168
	s_waitcnt lgkmcnt(0)
	v_fmac_f32_e32 v80, v96, v76
	v_fmac_f32_e32 v80, v97, v77
	v_fmac_f32_e32 v80, v98, v78
	v_fmac_f32_e32 v80, v99, v79
	ds_read_b128 v[76:79], v88 offset:65184
	s_waitcnt lgkmcnt(0)
	v_fmac_f32_e32 v80, v100, v76
	v_fmac_f32_e32 v80, v101, v77
	v_fmac_f32_e32 v80, v102, v78
	v_fmac_f32_e32 v80, v103, v79
	ds_read_b128 v[76:79], v88 offset:65200
	s_waitcnt lgkmcnt(0)
	v_fmac_f32_e32 v80, v104, v76
	v_fmac_f32_e32 v80, v105, v77
	v_fmac_f32_e32 v80, v106, v78
	v_fmac_f32_e32 v80, v107, v79
	v_mul_f32_e64 v77, |v80|, s55
	v_exp_f32_e32 v77, v77
	v_min_f32_e32 v76, 0, v80
	v_add_f32_e32 v77, 1.0, v77
	v_cmp_gt_f32_e64 s[40:41], s33, v77
	s_nop 1
	v_cndmask_b32_e64 v78, 0, 32, s[40:41]
	v_ldexp_f32 v77, v77, v78
	v_log_f32_e32 v77, v77
	s_nop 0
	v_mul_f32_e32 v78, 0x3f317217, v77
	v_fma_f32 v78, v77, s57, -v78
	v_fmac_f32_e32 v78, 0x3377d1cf, v77
	v_fmac_f32_e32 v78, 0x3f317217, v77
	v_cmp_lt_f32_e64 s[42:43], |v77|, s58
	s_nop 1
	v_cndmask_b32_e64 v77, v77, v78, s[42:43]
	v_cndmask_b32_e64 v78, 0, v229, s[40:41]
	v_sub_f32_e32 v77, v77, v78
	v_sub_f32_e32 v110, v76, v77
	ds_read_b128 v[76:79], v88 offset:65088
	s_waitcnt lgkmcnt(0)
	v_fma_f32 v80, v67, v76, v108
	v_fmac_f32_e32 v80, v93, v77
	v_fmac_f32_e32 v80, v94, v78
	v_fmac_f32_e32 v80, v95, v79
	ds_read_b128 v[76:79], v88 offset:65104
	s_waitcnt lgkmcnt(0)
	v_fmac_f32_e32 v80, v96, v76
	v_fmac_f32_e32 v80, v97, v77
	v_fmac_f32_e32 v80, v98, v78
	v_fmac_f32_e32 v80, v99, v79
	ds_read_b128 v[76:79], v88 offset:65120
	s_waitcnt lgkmcnt(0)
	v_fmac_f32_e32 v80, v100, v76
	v_fmac_f32_e32 v80, v101, v77
	v_fmac_f32_e32 v80, v102, v78
	v_fmac_f32_e32 v80, v103, v79
	ds_read_b128 v[76:79], v88 offset:65136
	s_waitcnt lgkmcnt(0)
	v_fmac_f32_e32 v80, v104, v76
	v_fmac_f32_e32 v80, v105, v77
	v_fmac_f32_e32 v80, v106, v78
	v_fmac_f32_e32 v80, v107, v79
	v_mul_f32_e64 v77, |v80|, s55
	v_exp_f32_e32 v77, v77
	v_min_f32_e32 v76, 0, v80
	v_add_f32_e32 v77, 1.0, v77
	v_cmp_gt_f32_e64 s[40:41], s33, v77
	s_nop 1
	v_cndmask_b32_e64 v78, 0, 32, s[40:41]
	v_ldexp_f32 v77, v77, v78
	v_log_f32_e32 v77, v77
	s_nop 0
	v_mul_f32_e32 v78, 0x3f317217, v77
	v_fma_f32 v78, v77, s57, -v78
	v_fmac_f32_e32 v78, 0x3377d1cf, v77
	v_fmac_f32_e32 v78, 0x3f317217, v77
	v_cmp_lt_f32_e64 s[42:43], |v77|, s58
	s_nop 1
	v_cndmask_b32_e64 v77, v77, v78, s[42:43]
	v_cndmask_b32_e64 v78, 0, v229, s[40:41]
	v_sub_f32_e32 v77, v77, v78
	v_sub_f32_e32 v111, v76, v77
	ds_read_b128 v[76:79], v88 offset:65024
	s_waitcnt lgkmcnt(0)
	v_fma_f32 v80, v67, v76, v108
	v_fmac_f32_e32 v80, v93, v77
	v_fmac_f32_e32 v80, v94, v78
	v_fmac_f32_e32 v80, v95, v79
	ds_read_b128 v[76:79], v88 offset:65040
	s_waitcnt lgkmcnt(0)
	v_fmac_f32_e32 v80, v96, v76
	v_fmac_f32_e32 v80, v97, v77
	v_fmac_f32_e32 v80, v98, v78
	v_fmac_f32_e32 v80, v99, v79
	ds_read_b128 v[76:79], v88 offset:65056
	s_waitcnt lgkmcnt(0)
	v_fmac_f32_e32 v80, v100, v76
	v_fmac_f32_e32 v80, v101, v77
	v_fmac_f32_e32 v80, v102, v78
	v_fmac_f32_e32 v80, v103, v79
	ds_read_b128 v[76:79], v88 offset:65072
	s_waitcnt lgkmcnt(0)
	v_fmac_f32_e32 v80, v104, v76
	v_fmac_f32_e32 v80, v105, v77
	v_fmac_f32_e32 v80, v106, v78
	v_fmac_f32_e32 v80, v107, v79
	v_mul_f32_e64 v77, |v80|, s55
	v_exp_f32_e32 v77, v77
	v_min_f32_e32 v76, 0, v80
	v_add_f32_e32 v77, 1.0, v77
	v_cmp_gt_f32_e64 s[40:41], s33, v77
	s_nop 1
	v_cndmask_b32_e64 v78, 0, 32, s[40:41]
	v_ldexp_f32 v77, v77, v78
	v_log_f32_e32 v77, v77
	s_nop 0
	v_mul_f32_e32 v78, 0x3f317217, v77
	v_fma_f32 v78, v77, s57, -v78
	v_fmac_f32_e32 v78, 0x3377d1cf, v77
	v_fmac_f32_e32 v78, 0x3f317217, v77
	v_cmp_lt_f32_e64 s[42:43], |v77|, s58
	s_nop 1
	v_cndmask_b32_e64 v77, v77, v78, s[42:43]
	v_cndmask_b32_e64 v78, 0, v229, s[40:41]
	v_sub_f32_e32 v77, v77, v78
	v_sub_f32_e32 v112, v76, v77
	ds_read_b128 v[76:79], v88 offset:64960
	s_waitcnt lgkmcnt(0)
; __device__ __forceinline__ void gla_decay(unsigned char* lds, const float* glow_t0, const float* Wg  , const float* bg  , int dir) {
;     ...
;     for (int k = 0; k < 8; ++k) { const float* gl = GLs + (seg * 8 + k) * 16; float a = bias;
; #pragma unroll
;         for (int r = 0; r < 16; ++r) a += gl[r] * w[r];
;         loc[k] = (fminf(a, 0.f) - __logf(1.f + __expf(-fabsf(a)))) * (1.f / 16.f); }
;     float run = 0.f;
;     if (dir == 0) {
; #pragma unroll
;         for (int k = 0; k < 8; ++k) { run += loc[k]; loc[k] = run; }
;     } else {
; #pragma unroll
;         for (int k = 7; k >= 0; --k) { run += loc[k]; loc[k] = run; }
;     }
;     Tot[seg * 64 + d] = run;
	v_fma_f32 v80, v67, v76, v108
	v_fmac_f32_e32 v80, v93, v77
	v_fmac_f32_e32 v80, v94, v78
	v_fmac_f32_e32 v80, v95, v79
	ds_read_b128 v[76:79], v88 offset:64976
	s_waitcnt lgkmcnt(0)
	v_fmac_f32_e32 v80, v96, v76
	v_fmac_f32_e32 v80, v97, v77
	v_fmac_f32_e32 v80, v98, v78
	v_fmac_f32_e32 v80, v99, v79
	ds_read_b128 v[76:79], v88 offset:64992
	s_waitcnt lgkmcnt(0)
	v_fmac_f32_e32 v80, v100, v76
	v_fmac_f32_e32 v80, v101, v77
	v_fmac_f32_e32 v80, v102, v78
	v_fmac_f32_e32 v80, v103, v79
	ds_read_b128 v[76:79], v88 offset:65008
	s_waitcnt lgkmcnt(0)
	v_fmac_f32_e32 v80, v104, v76
	v_fmac_f32_e32 v80, v105, v77
	v_fmac_f32_e32 v80, v106, v78
	v_fmac_f32_e32 v80, v107, v79
	v_mul_f32_e64 v77, |v80|, s55
	v_exp_f32_e32 v77, v77
	v_min_f32_e32 v76, 0, v80
	v_add_f32_e32 v77, 1.0, v77
	v_cmp_gt_f32_e64 s[40:41], s33, v77
	s_nop 1
	v_cndmask_b32_e64 v78, 0, 32, s[40:41]
	v_ldexp_f32 v77, v77, v78
	v_log_f32_e32 v77, v77
	s_nop 0
	v_mul_f32_e32 v78, 0x3f317217, v77
	v_fma_f32 v78, v77, s57, -v78
	v_fmac_f32_e32 v78, 0x3377d1cf, v77
	v_fmac_f32_e32 v78, 0x3f317217, v77
	v_cmp_lt_f32_e64 s[42:43], |v77|, s58
	s_nop 1
	v_cndmask_b32_e64 v77, v77, v78, s[42:43]
	v_cndmask_b32_e64 v78, 0, v229, s[40:41]
	v_sub_f32_e32 v77, v77, v78
	v_sub_f32_e32 v113, v76, v77
	ds_read_b128 v[76:79], v88 offset:64896
	s_waitcnt lgkmcnt(0)
	v_fma_f32 v80, v67, v76, v108
	v_fmac_f32_e32 v80, v93, v77
	v_fmac_f32_e32 v80, v94, v78
	v_fmac_f32_e32 v80, v95, v79
	ds_read_b128 v[76:79], v88 offset:64912
	s_waitcnt lgkmcnt(0)
	v_fmac_f32_e32 v80, v96, v76
	v_fmac_f32_e32 v80, v97, v77
	v_fmac_f32_e32 v80, v98, v78
	v_fmac_f32_e32 v80, v99, v79
	ds_read_b128 v[76:79], v88 offset:64928
	s_waitcnt lgkmcnt(0)
	v_fmac_f32_e32 v80, v100, v76
	v_fmac_f32_e32 v80, v101, v77
	v_fmac_f32_e32 v80, v102, v78
	v_fmac_f32_e32 v80, v103, v79
	ds_read_b128 v[76:79], v88 offset:64944
	s_waitcnt lgkmcnt(0)
	v_fmac_f32_e32 v80, v104, v76
	v_fmac_f32_e32 v80, v105, v77
	v_fmac_f32_e32 v80, v106, v78
	v_fmac_f32_e32 v80, v107, v79
	v_mul_f32_e64 v77, |v80|, s55
	v_exp_f32_e32 v77, v77
	v_min_f32_e32 v76, 0, v80
	v_add_f32_e32 v77, 1.0, v77
	v_cmp_gt_f32_e64 s[40:41], s33, v77
	s_nop 1
	v_cndmask_b32_e64 v78, 0, 32, s[40:41]
	v_ldexp_f32 v77, v77, v78
	v_log_f32_e32 v77, v77
	s_nop 0
	v_mul_f32_e32 v78, 0x3f317217, v77
	v_fma_f32 v78, v77, s57, -v78
	v_fmac_f32_e32 v78, 0x3377d1cf, v77
	v_fmac_f32_e32 v78, 0x3f317217, v77
	v_cmp_lt_f32_e64 s[42:43], |v77|, s58
	s_nop 1
	v_cndmask_b32_e64 v77, v77, v78, s[42:43]
	v_cndmask_b32_e64 v78, 0, v229, s[40:41]
	v_sub_f32_e32 v77, v77, v78
	v_sub_f32_e32 v114, v76, v77
	ds_read_b128 v[76:79], v88 offset:64832
	s_waitcnt lgkmcnt(0)
	v_fma_f32 v80, v67, v76, v108
	v_fmac_f32_e32 v80, v93, v77
	v_fmac_f32_e32 v80, v94, v78
	v_fmac_f32_e32 v80, v95, v79
	ds_read_b128 v[76:79], v88 offset:64848
	s_waitcnt lgkmcnt(0)
	v_fmac_f32_e32 v80, v96, v76
	v_fmac_f32_e32 v80, v97, v77
	v_fmac_f32_e32 v80, v98, v78
	v_fmac_f32_e32 v80, v99, v79
	ds_read_b128 v[76:79], v88 offset:64864
	s_waitcnt lgkmcnt(0)
	v_fmac_f32_e32 v80, v100, v76
	v_fmac_f32_e32 v80, v101, v77
	v_fmac_f32_e32 v80, v102, v78
	v_fmac_f32_e32 v80, v103, v79
	ds_read_b128 v[76:79], v88 offset:64880
	s_waitcnt lgkmcnt(0)
	v_fmac_f32_e32 v80, v104, v76
	v_fmac_f32_e32 v80, v105, v77
	v_fmac_f32_e32 v80, v106, v78
	v_fmac_f32_e32 v80, v107, v79
	v_mul_f32_e64 v77, |v80|, s55
	v_exp_f32_e32 v77, v77
	v_min_f32_e32 v76, 0, v80
	v_add_f32_e32 v77, 1.0, v77
	v_cmp_gt_f32_e64 s[40:41], s33, v77
	s_nop 1
	v_cndmask_b32_e64 v78, 0, 32, s[40:41]
	v_ldexp_f32 v77, v77, v78
	v_log_f32_e32 v77, v77
	s_nop 0
	v_mul_f32_e32 v78, 0x3f317217, v77
	v_fma_f32 v78, v77, s57, -v78
	v_fmac_f32_e32 v78, 0x3377d1cf, v77
	v_fmac_f32_e32 v78, 0x3f317217, v77
	v_cmp_lt_f32_e64 s[42:43], |v77|, s58
	s_nop 1
	v_cndmask_b32_e64 v77, v77, v78, s[42:43]
	v_cndmask_b32_e64 v78, 0, v229, s[40:41]
	v_sub_f32_e32 v77, v77, v78
	v_sub_f32_e32 v115, v76, v77
	ds_read_b128 v[76:79], v88 offset:64768
	ds_read_b128 v[80:83], v88 offset:64784
	ds_read_b128 v[84:87], v88 offset:64800
	ds_read_b128 v[88:91], v88 offset:64816
	s_waitcnt lgkmcnt(3)
	v_fmac_f32_e32 v108, v67, v76
	v_fmac_f32_e32 v108, v93, v77
	v_fmac_f32_e32 v108, v94, v78
	v_fmac_f32_e32 v108, v95, v79
	s_waitcnt lgkmcnt(2)
	v_fmac_f32_e32 v108, v96, v80
	v_fmac_f32_e32 v108, v97, v81
	v_fmac_f32_e32 v108, v98, v82
	v_fmac_f32_e32 v108, v99, v83
	s_waitcnt lgkmcnt(1)
	v_fmac_f32_e32 v108, v100, v84
	v_fmac_f32_e32 v108, v101, v85
	v_fmac_f32_e32 v108, v102, v86
	v_fmac_f32_e32 v108, v103, v87
	s_waitcnt lgkmcnt(0)
	v_fmac_f32_e32 v108, v104, v88
	v_fmac_f32_e32 v108, v105, v89
	v_fmac_f32_e32 v108, v106, v90
	v_fmac_f32_e32 v108, v107, v91
	v_mul_f32_e64 v76, |v108|, s55
	v_exp_f32_e32 v76, v76
	v_fma_f32 v78, v109, s62, 0
	v_fmamk_f32 v79, v110, 0x3d800000, v78
	v_fmamk_f32 v80, v111, 0x3d800000, v79
	v_add_f32_e32 v76, 1.0, v76
	v_cmp_gt_f32_e64 s[40:41], s33, v76
	v_fmamk_f32 v81, v112, 0x3d800000, v80
	v_fmamk_f32 v82, v113, 0x3d800000, v81
	v_cndmask_b32_e64 v77, 0, 32, s[40:41]
	v_ldexp_f32 v76, v76, v77
	v_log_f32_e32 v76, v76
	v_min_f32_e32 v67, 0, v108
	v_fmamk_f32 v83, v114, 0x3d800000, v82
	v_fmamk_f32 v84, v115, 0x3d800000, v83
	v_mul_f32_e32 v77, 0x3f317217, v76
	v_fma_f32 v77, v76, s57, -v77
	v_fmac_f32_e32 v77, 0x3377d1cf, v76
	v_fmac_f32_e32 v77, 0x3f317217, v76
	v_cmp_lt_f32_e64 s[42:43], |v76|, s58
	s_nop 1
	v_cndmask_b32_e64 v76, v76, v77, s[42:43]
	v_cndmask_b32_e64 v77, 0, v229, s[40:41]
	v_sub_f32_e32 v76, v76, v77
	v_sub_f32_e32 v67, v67, v76
	v_fmamk_f32 v67, v67, 0x3d800000, v84
	v_add_u32_e32 v76, 0, v92
	ds_write_b32 v76, v67 offset:16640
	s_waitcnt lgkmcnt(0)
	s_barrier
; __device__ __forceinline__ unsigned f2bf(float f) { unsigned u = __float_as_uint(f); return (u + 0x7fffu + ((u >> 16) & 1u)) >> 16; }
; __device__ __forceinline__ u32x4 pack8(const float* v) { u32x4 w; w.x = pk2(v[0], v[1]); w.y = pk2(v[2], v[3]); w.z = pk2(v[4], v[5]); w.w = pk2(v[6], v[7]); return w; }
; __device__ __forceinline__ void unpack8(u32x4 w, float* v) { v[0] = bflo(w.x); v[1] = bfhi(w.x); v[2] = bflo(w.y); v[3] = bfhi(w.y); v[4] = bflo(w.z); v[5] = bfhi(w.z); v[6] = bflo(w.w); v[7] = bfhi(w.w); }
; __device__ __forceinline__ void gla_decay(unsigned char* lds, const float* glow_t0, const float* Wg  , const float* bg  , int dir) {
;     ...
;     float off = 0.f;
; #pragma unroll
;     for (int sg = 0; sg < 8; ++sg) { const float tv = Tot[sg * 64 + d]; if (dir == 0 ? (sg < seg) : (sg > seg)) off += tv; }
; #pragma unroll
;     for (int k = 0; k < 8; ++k) Bs[(seg * 8 + k) * 65 + d] = loc[k] + off;
;     __syncthreads();
; __device__ __forceinline__ void gla_out_item(unsigned char* lds, unsigned char* ws, const float* wgate, const float* bgate, const float* hnorm, int l, int item, bool dowrite = true) {
;     ...
;         { const int s = tid >> 3, dg = tid & 7;
;           float qv[8], kv[8];
;           unpack8(qraw, qv);
;           unpack8(kraw, kv);
; #pragma unroll
;           for (int e = 0; e < 8; ++e) { const float bv = Bs[s * 65 + dg * 8 + e]; qv[e] *= __expf(bv); kv[e] *= __expf(-bv); }
;           *(u32x4*)(QE + s * 72 + dg * 8) = pack8(qv); *(u32x4*)(KE + s * 72 + dg * 8) = pack8(kv); }
;         __syncthreads();
;         { const int rb = wid >> 1;
; #pragma unroll
;           for (int cc = 0; cc < 2; ++cc) { const int cb = (wid & 1) * 2 + cc; f32x4 a4 = (f32x4){0.f, 0.f, 0.f, 0.f};
; #pragma unroll
;               for (int kk = 0; kk < 2; ++kk) { const bf16x8 a = *(const bf16x8*)(QE + (rb * 16 + ql) * 72 + kk * 32 + g * 8); const bf16x8 bb = *(const bf16x8*)(KE + (cb * 16 + ql) * 72 + kk * 32 + g * 8);
;                   a4 = __builtin_amdgcn_mfma_f32_16x16x32_bf16(a, bb, a4, 0, 0, 0); }
; #pragma unroll
;               for (int j = 0; j < 4; ++j) { const int i = rb * 16 + g * 4 + j, ip = cb * 16 + ql; const bool keep = dir == 0 ? (ip <= i) : (ip >= i); ATT[i * 72 + ip] = (bf16_t)f2bf(keep ? a4[j] : 0.f); } } }
	ds_read2st64_b32 v[76:77], v66 offset0:65 offset1:66
	v_cmp_gt_i32_e64 s[40:41], 0, v75
	s_waitcnt lgkmcnt(0)
	v_add_f32_e32 v76, 0, v76
	v_cndmask_b32_e64 v76, 0, v76, s[40:41]
	v_cmp_gt_i32_e64 s[40:41], 1, v75
	v_add_f32_e32 v76, v77, v76
	s_nop 0
	v_cndmask_b32_e64 v85, 0, v76, s[40:41]
	ds_read2st64_b32 v[76:77], v66 offset0:67 offset1:68
	v_cmp_gt_i32_e64 s[40:41], 2, v75
	s_waitcnt lgkmcnt(0)
	v_add_f32_e32 v76, v76, v85
	v_cndmask_b32_e64 v76, 0, v76, s[40:41]
	v_cmp_gt_i32_e64 s[40:41], 3, v75
	v_add_f32_e32 v76, v77, v76
	s_nop 0
	v_cndmask_b32_e64 v85, 0, v76, s[40:41]
	ds_read2st64_b32 v[76:77], v66 offset0:69 offset1:70
	v_cmp_gt_i32_e64 s[40:41], 4, v75
	s_waitcnt lgkmcnt(0)
	v_add_f32_e32 v76, v76, v85
	v_cndmask_b32_e64 v76, 0, v76, s[40:41]
	v_cmp_gt_i32_e64 s[40:41], 5, v75
	v_add_f32_e32 v76, v77, v76
	s_nop 0
	v_cndmask_b32_e64 v85, 0, v76, s[40:41]
	ds_read2st64_b32 v[76:77], v66 offset0:71 offset1:72
	v_cmp_gt_i32_e64 s[40:41], 6, v75
	s_waitcnt lgkmcnt(0)
	v_add_f32_e32 v76, v76, v85
	v_cndmask_b32_e64 v76, 0, v76, s[40:41]
	v_cmp_gt_i32_e64 s[40:41], 7, v75
	v_add_f32_e32 v76, v77, v76
	s_nop 0
	v_cndmask_b32_e64 v76, 0, v76, s[40:41]
	v_add_f32_e32 v77, v67, v76
	v_mad_u64_u32 v[66:67], s[0:1], v75, s59, v[66:67]
	v_add_f32_e32 v67, v84, v76
	ds_write2_b32 v66, v77, v67 offset1:65
	v_add_f32_e32 v67, v83, v76
	v_add_f32_e32 v75, v82, v76
	ds_write2_b32 v66, v67, v75 offset0:130 offset1:195
	v_add_f32_e32 v67, v81, v76
	v_add_f32_e32 v75, v80, v76
	v_add_u32_e32 v66, 0x400, v66
	ds_write2_b32 v66, v67, v75 offset0:4 offset1:69
	v_add_f32_e32 v67, v79, v76
	v_add_f32_e32 v75, v78, v76
	ds_write2_b32 v66, v67, v75 offset0:134 offset1:199
	s_waitcnt lgkmcnt(0)
	s_barrier
	ds_read2_b32 v[66:67], v48 offset1:1
	v_cmp_ge_i32_e64 s[40:41], v71, v39
	s_movk_i32 s0, 0x210
	s_waitcnt lgkmcnt(0)
	v_mul_f32_e32 v75, 0x3fb8aa3b, v66
	v_exp_f32_e32 v76, v75
	v_mul_f32_e32 v66, 0xbfb8aa3b, v66
	v_mul_f32_e32 v75, 0x3fb8aa3b, v67
	v_mul_f32_e32 v67, 0xbfb8aa3b, v67
	v_exp_f32_e32 v66, v66
	v_exp_f32_e32 v67, v67
	v_exp_f32_e32 v77, v75
	v_pk_mul_f32 v[66:67], v[66:67], v[52:53]
	ds_read2_b32 v[52:53], v48 offset0:2 offset1:3
	v_pk_mul_f32 v[50:51], v[76:77], v[50:51]
	s_waitcnt lgkmcnt(0)
	v_mul_f32_e32 v75, 0x3fb8aa3b, v52
	v_exp_f32_e32 v76, v75
	v_mul_f32_e32 v52, 0xbfb8aa3b, v52
	v_mul_f32_e32 v75, 0x3fb8aa3b, v53
	v_mul_f32_e32 v53, 0xbfb8aa3b, v53
	v_exp_f32_e32 v52, v52
	v_exp_f32_e32 v53, v53
	v_exp_f32_e32 v77, v75
	v_cvt_pk_bf16_f32 v50, v50, v51
	v_pk_mul_f32 v[56:57], v[52:53], v[56:57]
	ds_read2_b32 v[52:53], v48 offset0:4 offset1:5
	v_pk_mul_f32 v[54:55], v[76:77], v[54:55]
	s_waitcnt lgkmcnt(0)
	v_mul_f32_e32 v75, 0x3fb8aa3b, v52
	v_exp_f32_e32 v76, v75
	v_mul_f32_e32 v52, 0xbfb8aa3b, v52
	v_mul_f32_e32 v75, 0x3fb8aa3b, v53
	v_mul_f32_e32 v53, 0xbfb8aa3b, v53
	v_exp_f32_e32 v52, v52
	v_exp_f32_e32 v53, v53
	v_exp_f32_e32 v77, v75
	v_cvt_pk_bf16_f32 v51, v54, v55
	v_pk_mul_f32 v[60:61], v[52:53], v[60:61]
	ds_read2_b32 v[52:53], v48 offset0:6 offset1:7
	v_pk_mul_f32 v[58:59], v[76:77], v[58:59]
	s_waitcnt lgkmcnt(0)
	v_mul_f32_e32 v48, 0x3fb8aa3b, v52
	v_exp_f32_e32 v76, v48
	v_mul_f32_e32 v48, 0xbfb8aa3b, v52
	v_exp_f32_e32 v52, v48
	v_mul_f32_e32 v48, 0x3fb8aa3b, v53
	v_exp_f32_e32 v77, v48
	v_mul_f32_e32 v48, 0xbfb8aa3b, v53
	v_exp_f32_e32 v53, v48
	v_pk_mul_f32 v[62:63], v[76:77], v[62:63]
	v_pk_mul_f32 v[64:65], v[52:53], v[64:65]
	v_cvt_pk_bf16_f32 v52, v58, v59
	v_cvt_pk_bf16_f32 v53, v62, v63
	ds_write_b128 v42, v[50:53] offset:18688
	v_cvt_pk_bf16_f32 v50, v66, v67
	v_cvt_pk_bf16_f32 v51, v56, v57
	v_cvt_pk_bf16_f32 v52, v60, v61
	v_cvt_pk_bf16_f32 v53, v64, v65
	ds_write_b128 v42, v[50:53] offset:27904
	s_waitcnt lgkmcnt(0)
	s_barrier
	ds_read_b128 v[50:53], v38 offset:18688
	ds_read_b128 v[54:57], v49 offset:27904
	s_waitcnt lgkmcnt(0)
	v_mfma_f32_16x16x32_bf16 v[50:53], v[50:53], v[54:57], 0
	ds_read_b128 v[54:57], v38 offset:18752
	ds_read_b128 v[58:61], v49 offset:27968
	v_and_b32_e32 v67, 0xffff0000, v0
	s_waitcnt lgkmcnt(0)
	v_mfma_f32_16x16x32_bf16 v[50:53], v[54:57], v[58:61], v[50:53]
	s_nop 7
	v_cndmask_b32_e64 v42, 0, v50, s[40:41]
	v_bfe_u32 v48, v42, 16, 1
	v_add3_u32 v42, v42, v48, s86
	ds_write_b16_d16_hi v43, v42 offset:37120
	v_cndmask_b32_e32 v42, 0, v51, vcc
	v_bfe_u32 v48, v42, 16, 1
	v_add3_u32 v42, v42, v48, s86
	v_cmp_ge_i32_e32 vcc, v71, v72
	ds_write_b16_d16_hi v43, v42 offset:37264
	s_nop 0
	v_cndmask_b32_e32 v42, 0, v52, vcc
	v_bfe_u32 v48, v42, 16, 1
	v_add3_u32 v42, v42, v48, s86
	v_cmp_ge_i32_e32 vcc, v71, v73
	ds_write_b16_d16_hi v43, v42 offset:37408
	s_nop 0
	v_cndmask_b32_e32 v42, 0, v53, vcc
	v_bfe_u32 v48, v42, 16, 1
	v_add3_u32 v42, v42, v48, s86
	ds_write_b16_d16_hi v43, v42 offset:37552
	ds_read_b128 v[50:53], v38 offset:18688
	ds_read_b128 v[54:57], v49 offset:30208
	s_waitcnt lgkmcnt(0)
	v_mfma_f32_16x16x32_bf16 v[50:53], v[50:53], v[54:57], 0
	ds_read_b128 v[54:57], v38 offset:18752
	ds_read_b128 v[58:61], v49 offset:30272
	v_cmp_ge_i32_e32 vcc, v74, v39
	v_lshlrev_b32_e32 v42, 16, v6
	s_waitcnt lgkmcnt(0)
	v_mfma_f32_16x16x32_bf16 v[48:51], v[54:57], v[58:61], v[50:53]
	s_nop 7
	v_cndmask_b32_e32 v38, 0, v48, vcc
	v_bfe_u32 v39, v38, 16, 1
	v_add3_u32 v38, v38, v39, s86
	ds_write_b16_d16_hi v43, v38 offset:37152
	v_cndmask_b32_e64 v38, 0, v49, s[38:39]
	v_bfe_u32 v39, v38, 16, 1
	v_add3_u32 v38, v38, v39, s86
	v_cmp_ge_i32_e32 vcc, v74, v72
	ds_write_b16_d16_hi v43, v38 offset:37296
	s_nop 0
	v_cndmask_b32_e32 v38, 0, v50, vcc
	v_bfe_u32 v39, v38, 16, 1
	v_add3_u32 v38, v38, v39, s86
	v_cmp_ge_i32_e32 vcc, v74, v73
	ds_write_b16_d16_hi v43, v38 offset:37440
	s_nop 0
	v_cndmask_b32_e32 v38, 0, v51, vcc
	v_bfe_u32 v39, v38, 16, 1
	v_add3_u32 v38, v38, v39, s86
	ds_write_b16_d16_hi v43, v38 offset:37584
	s_waitcnt lgkmcnt(0)
	s_barrier
; __device__ __forceinline__ void gla_out_item(unsigned char* lds, unsigned char* ws, const float* wgate, const float* bgate, const float* hnorm, int l, int item, bool dowrite = true) {
;     ...
;         { const int sidx = ((b * 4 + h) * 2 + dir) * 132 + c;
;           const bf16_t* st = (const bf16_t*)(ws + O_ST) + (size_t)sidx * 8192;
; #pragma unroll
;           for (int kk = 0; kk < 2; ++kk) {
;               const bf16x8 bv = *(const bf16x8*)(Vt + (wid * 16 + ql) * 72 + kk * 32 + g * 8);
;               const bf16x8 bs = dir == 0 ? sfr[0][kk] : sfr[1][kk];
; #pragma unroll
;               for (int rb = 0; rb < 4; ++rb) {
;                   const bf16x8 a1 = *(const bf16x8*)(ATT + (rb * 16 + ql) * 72 + kk * 32 + g * 8);
;                   const bf16x8 a2 = *(const bf16x8*)(QE + (rb * 16 + ql) * 72 + kk * 32 + g * 8);
;                   oacc[rb] = __builtin_amdgcn_mfma_f32_16x16x32_bf16(a1, bv, oacc[rb], 0, 0, 0);
;                   oacc[rb] = __builtin_amdgcn_mfma_f32_16x16x32_bf16(a2, bs, oacc[rb], 0, 0, 0);
;               } } }
;         __syncthreads();
;     }
;     float* Os = (float*)(lds + GL_O);
; #pragma unroll
;     for (int rb = 0; rb < 4; ++rb)
; #pragma unroll
;         for (int j = 0; j < 4; ++j) Os[(rb * 16 + g * 4 + j) * 132 + wid * 16 + ql] = oacc[rb][j];
;     __syncthreads();
	ds_read_b128 v[48:51], v34 offset:46336
	ds_read_b128 v[52:55], v35 offset:37120
	ds_read_b128 v[56:59], v35 offset:18688
	s_waitcnt lgkmcnt(1)
	v_mfma_f32_16x16x32_bf16 v[16:19], v[52:55], v[48:51], v[16:19]
	v_and_b32_e32 v43, 0xffff0000, v6
	v_mul_f32_e32 v6, 0xbfb8aa3b, v42
	v_exp_f32_e32 v6, v6
	s_waitcnt lgkmcnt(0)
	v_mfma_f32_16x16x32_bf16 v[16:19], v[56:59], v[12:15], v[16:19]
	ds_read_b128 v[52:55], v35 offset:39424
	ds_read_b128 v[56:59], v35 offset:20992
	v_cmp_lt_i32_e32 vcc, v220, v219
	s_waitcnt lgkmcnt(1)
	v_mfma_f32_16x16x32_bf16 v[20:23], v[52:55], v[48:51], v[20:23]
	s_waitcnt lgkmcnt(0)
	v_mfma_f32_16x16x32_bf16 v[20:23], v[56:59], v[12:15], v[20:23]
	ds_read_b128 v[52:55], v35 offset:41728
	ds_read_b128 v[56:59], v35 offset:23296
	s_waitcnt lgkmcnt(1)
	v_mfma_f32_16x16x32_bf16 v[24:27], v[52:55], v[48:51], v[24:27]
	s_waitcnt lgkmcnt(0)
	v_mfma_f32_16x16x32_bf16 v[24:27], v[56:59], v[12:15], v[24:27]
	ds_read_b128 v[52:55], v35 offset:44032
	ds_read_b128 v[56:59], v35 offset:25600
	s_waitcnt lgkmcnt(1)
	v_mfma_f32_16x16x32_bf16 v[28:31], v[52:55], v[48:51], v[28:31]
	s_waitcnt lgkmcnt(0)
	v_mfma_f32_16x16x32_bf16 v[12:15], v[56:59], v[12:15], v[28:31]
	s_nop 5
	ds_read_b128 v[28:31], v34 offset:46400
	ds_read_b128 v[48:51], v35 offset:37184
	ds_read_b128 v[52:55], v35 offset:18752
	s_waitcnt lgkmcnt(1)
	v_mfma_f32_16x16x32_bf16 v[16:19], v[48:51], v[28:31], v[16:19]
	s_waitcnt lgkmcnt(0)
	v_mfma_f32_16x16x32_bf16 v[16:19], v[52:55], v[8:11], v[16:19]
	ds_read_b128 v[48:51], v35 offset:39488
	ds_read_b128 v[52:55], v35 offset:21056
	s_waitcnt lgkmcnt(1)
	v_mfma_f32_16x16x32_bf16 v[20:23], v[48:51], v[28:31], v[20:23]
	s_waitcnt lgkmcnt(0)
	v_mfma_f32_16x16x32_bf16 v[20:23], v[52:55], v[8:11], v[20:23]
	ds_read_b128 v[48:51], v35 offset:41792
	ds_read_b128 v[52:55], v35 offset:23360
	s_waitcnt lgkmcnt(1)
	v_mfma_f32_16x16x32_bf16 v[24:27], v[48:51], v[28:31], v[24:27]
	s_waitcnt lgkmcnt(0)
	v_mfma_f32_16x16x32_bf16 v[24:27], v[52:55], v[8:11], v[24:27]
	ds_read_b128 v[48:51], v35 offset:44096
	ds_read_b128 v[52:55], v35 offset:25664
	s_waitcnt lgkmcnt(0)
	s_barrier
	v_mfma_f32_16x16x32_bf16 v[12:15], v[48:51], v[28:31], v[12:15]
	v_lshlrev_b32_e32 v28, 6, v41
	v_and_b32_e32 v41, 0xffff0000, v7
	v_mfma_f32_16x16x32_bf16 v[8:11], v[52:55], v[8:11], v[12:15]
	v_cndmask_b32_e32 v29, v218, v220, vcc
	v_cmp_lt_i32_e32 vcc, v221, v219
	v_lshlrev_b32_e32 v29, 2, v29
	s_nop 1
	v_and_b32_e32 v12, 0xffffffc0, v68
	v_add_u32_e32 v12, 0, v12
	v_lshlrev_b32_e32 v13, 2, v69
	v_mul_u32_u24_e32 v14, 0x840, v70
	v_add3_u32 v12, v12, v13, v14
	v_add_u32_e32 v13, 0xfd00, v12
	v_add_u32_e32 v12, 0xfc00, v12
	ds_write2_b32 v12, v16, v17 offset0:64 offset1:196
	v_add_u32_e32 v12, 0x400, v13
	ds_write2_b32 v12, v18, v19 offset0:8 offset1:140
	v_add_u32_e32 v12, 0x2000, v13
	ds_write2_b32 v12, v20, v21 offset0:64 offset1:196
	v_add_u32_e32 v12, 0x2400, v13
	ds_write2_b32 v12, v22, v23 offset0:72 offset1:204
	v_add_u32_e32 v12, 0x4200, v13
	ds_write2_b32 v12, v24, v25 offset1:132
	v_add_u32_e32 v12, 0x4600, v13
	ds_write2_b32 v12, v26, v27 offset0:8 offset1:140
	v_add_u32_e32 v12, 0x6200, v13
	ds_write2_b32 v12, v8, v9 offset0:64 offset1:196
	v_add_u32_e32 v8, 0x6600, v13
	ds_write2_b32 v8, v10, v11 offset0:72 offset1:204
	v_mul_lo_u32 v8, v37, s0
	v_lshlrev_b32_e32 v37, 16, v7
	v_mul_f32_e32 v7, 0xbfb8aa3b, v43
	v_exp_f32_e32 v7, v7
	v_cndmask_b32_e32 v30, v218, v221, vcc
	v_cmp_lt_i32_e32 vcc, v222, v219
	s_lshl_b32 s0, s52, 9
	v_pk_add_f32 v[6:7], v[6:7], 1.0 op_sel_hi:[1,0]
	v_cndmask_b32_e32 v31, v218, v222, vcc
	s_add_u32 s0, s27, s0
	v_add3_u32 v8, 0, v8, v28
	s_addc_u32 s1, s36, 0
	v_rcp_f32_e32 v56, v7
	s_nop 0
	v_mul_f32_e32 v7, v43, v56
	s_waitcnt lgkmcnt(0)
	s_barrier
; __device__ __forceinline__ u32x4 pack8(const float* v) { u32x4 w; w.x = pk2(v[0], v[1]); w.y = pk2(v[2], v[3]); w.z = pk2(v[4], v[5]); w.w = pk2(v[6], v[7]); return w; }
; __device__ __forceinline__ void unpack8(u32x4 w, float* v) { v[0] = bflo(w.x); v[1] = bfhi(w.x); v[2] = bflo(w.y); v[3] = bfhi(w.y); v[4] = bflo(w.z); v[5] = bfhi(w.z); v[6] = bflo(w.w); v[7] = bfhi(w.w); }
; __device__ __forceinline__ float siluf_(float x) { return x / (1.f + __expf(-x)); }
; __device__ __forceinline__ void gla_out_item(unsigned char* lds, unsigned char* ws, const float* wgate, const float* bgate, const float* hnorm, int l, int item, bool dowrite = true) {
;     ...
;     { const int i = tid >> 3, eg = tid & 7;
;       float ov[16]; float ss = 0.f;
; #pragma unroll
;       for (int e = 0; e < 16; ++e) { ov[e] = Os[i * 132 + eg * 16 + e]; ss += ov[e] * ov[e]; }
;       ss += __shfl_xor(ss, 1); ss += __shfl_xor(ss, 2); ss += __shfl_xor(ss, 4);
;       const float rstd = rsqrtf(ss * (1.f / 128.f) + EPS);
;       const float* gn = hnorm + l * 512 + h * 128 + eg * 16;
;       bf16_t* rp = (bf16_t*)(ws + O_CR) + (size_t)(t0 + i) * 512 + h * 128 + eg * 16;
; #pragma unroll
;       for (int hh = 0; hh < 2; ++hh) { float rv[8]; unpack8(hh == 0 ? rraw0 : rraw1, rv);
; #pragma unroll
;           for (int e = 0; e < 8; ++e) rv[e] = ov[hh * 8 + e] * rstd * gn[hh * 8 + e] * siluf_(rv[e]);
;           if (dowrite) *(u32x4*)(rp + hh * 8) = pack8(rv); } }
;     __syncthreads();
	v_lshlrev_b32_e32 v58, 16, v5
	v_and_b32_e32 v5, 0xffff0000, v5
	v_mul_f32_e32 v56, 0xbfb8aa3b, v58
	v_mul_f32_e32 v57, 0xbfb8aa3b, v5
	v_exp_f32_e32 v56, v56
	v_exp_f32_e32 v57, v57
	ds_read_b128 v[20:23], v8 offset:64768
	ds_read_b128 v[16:19], v8 offset:64784
	ds_read_b128 v[12:15], v8 offset:64800
	ds_read_b128 v[8:11], v8 offset:64816
	global_load_dwordx4 v[48:51], v28, s[0:1] offset:16
	global_load_dwordx4 v[52:55], v28, s[0:1]
	global_load_dwordx4 v[134:137], v28, s[0:1] offset:48
	global_load_dwordx4 v[138:141], v28, s[0:1] offset:32
	v_rcp_f32_e32 v43, v6
	s_nop 0
	v_mul_f32_e32 v6, v42, v43
	v_pk_add_f32 v[56:57], v[56:57], 1.0 op_sel_hi:[1,0]
	s_waitcnt lgkmcnt(3)
	v_pk_mul_f32 v[42:43], v[22:23], v[22:23]
	s_waitcnt lgkmcnt(2)
	v_pk_mul_f32 v[38:39], v[16:17], v[16:17]
	v_pk_mul_f32 v[34:35], v[18:19], v[18:19]
	s_waitcnt lgkmcnt(0)
	v_pk_mul_f32 v[26:27], v[8:9], v[8:9]
	v_rcp_f32_e32 v59, v57
	s_nop 0
	v_mul_f32_e32 v57, v5, v59
	v_pk_mul_f32 v[24:25], v[10:11], v[10:11]
	v_lshlrev_b32_e32 v30, 2, v30
	v_lshlrev_b32_e32 v31, 2, v31
	v_lshlrev_b32_e32 v60, 16, v4
	v_and_b32_e32 v61, 0xffff0000, v4
	v_rcp_f32_e32 v5, v56
	s_nop 0
	v_mul_f32_e32 v56, v58, v5
	v_mul_f32_e32 v4, 0xbfb8aa3b, v60
	v_mul_f32_e32 v5, 0xbfb8aa3b, v61
	v_exp_f32_e32 v4, v4
	v_exp_f32_e32 v5, v5
	v_pk_mul_f32 v[58:59], v[20:21], v[20:21]
	s_add_i32 s98, s98, s97
	v_add_f32_e32 v58, v58, v59
	v_pk_add_f32 v[4:5], v[4:5], 1.0 op_sel_hi:[1,0]
	v_add_f32_e32 v42, v58, v42
	v_add_f32_e32 v42, v42, v43
	v_add_f32_e32 v38, v42, v38
	v_add_f32_e32 v38, v38, v39
	v_rcp_f32_e32 v62, v5
	s_nop 0
	v_mul_f32_e32 v5, v61, v62
	v_add_f32_e32 v34, v38, v34
	v_add_f32_e32 v34, v34, v35
	v_rcp_f32_e32 v61, v4
	s_nop 0
	v_mul_f32_e32 v4, v60, v61
	v_mul_f32_e32 v60, 0xbfb8aa3b, v37
	v_mul_f32_e32 v61, 0xbfb8aa3b, v41
	v_exp_f32_e32 v60, v60
	v_exp_f32_e32 v61, v61
	s_cmp_gt_i32 s98, s99
	v_pk_add_f32 v[60:61], v[60:61], 1.0 op_sel_hi:[1,0]
	s_nop 0
	s_nop 0
	v_rcp_f32_e32 v62, v61
	s_nop 0
	v_mul_f32_e32 v61, v41, v62
	v_lshlrev_b32_e32 v66, 16, v0
	v_mul_f32_e32 v0, 0xbfb8aa3b, v66
	v_exp_f32_e32 v0, v0
	v_rcp_f32_e32 v41, v60
	s_nop 0
	v_mul_f32_e32 v60, v37, v41
	v_lshlrev_b32_e32 v37, 16, v1
	v_and_b32_e32 v41, 0xffff0000, v1
	v_mul_f32_e32 v1, 0xbfb8aa3b, v67
	v_pk_mul_f32 v[64:65], v[12:13], v[12:13]
	v_exp_f32_e32 v1, v1
	v_add_f32_e32 v34, v34, v64
	v_pk_mul_f32 v[62:63], v[14:15], v[14:15]
	v_add_f32_e32 v34, v34, v65
	v_add_f32_e32 v34, v34, v62
	v_pk_add_f32 v[0:1], v[0:1], 1.0 op_sel_hi:[1,0]
	v_add_f32_e32 v34, v34, v63
	v_add_f32_e32 v26, v34, v26
	v_add_f32_e32 v26, v26, v27
	v_add_f32_e32 v24, v26, v24
	v_add_f32_e32 v24, v24, v25
	ds_bpermute_b32 v25, v29, v24
	s_waitcnt lgkmcnt(0)
	v_add_f32_e32 v24, v24, v25
	ds_bpermute_b32 v25, v30, v24
	v_rcp_f32_e32 v68, v1
	s_nop 0
	v_mul_f32_e32 v1, v67, v68
	s_waitcnt lgkmcnt(0)
	v_add_f32_e32 v24, v24, v25
	ds_bpermute_b32 v25, v31, v24
	s_waitcnt lgkmcnt(0)
	v_add_f32_e32 v24, v24, v25
	v_fmamk_f32 v24, v24, 0x3c000000, v216
	v_cmp_gt_f32_e32 vcc, s33, v24
	v_mul_f32_e32 v25, 0x4b800000, v24
	v_rcp_f32_e32 v67, v0
	s_nop 0
	v_mul_f32_e32 v0, v66, v67
	v_cndmask_b32_e32 v24, v24, v25, vcc
	v_rsq_f32_e32 v24, v24
	s_nop 0
	v_mul_f32_e32 v25, 0x45800000, v24
	v_cndmask_b32_e32 v24, v24, v25, vcc
	v_pk_mul_f32 v[20:21], v[20:21], v[24:25] op_sel_hi:[1,0]
	v_pk_mul_f32 v[16:17], v[16:17], v[24:25] op_sel_hi:[1,0]
	s_waitcnt vmcnt(0)
	v_pk_mul_f32 v[20:21], v[52:53], v[20:21]
	v_pk_mul_f32 v[16:17], v[48:49], v[16:17]
	v_pk_mul_f32 v[4:5], v[4:5], v[20:21]
	v_pk_mul_f32 v[20:21], v[22:23], v[24:25] op_sel_hi:[1,0]
	v_pk_mul_f32 v[6:7], v[6:7], v[16:17]
	v_pk_mul_f32 v[16:17], v[18:19], v[24:25] op_sel_hi:[1,0]
	v_pk_mul_f32 v[20:21], v[54:55], v[20:21]
	v_pk_mul_f32 v[16:17], v[50:51], v[16:17]
	v_pk_mul_f32 v[20:21], v[56:57], v[20:21]
	v_pk_mul_f32 v[16:17], v[60:61], v[16:17]
	v_cvt_pk_bf16_f32 v4, v4, v5
	v_cvt_pk_bf16_f32 v5, v20, v21
	v_cvt_pk_bf16_f32 v6, v6, v7
	v_cvt_pk_bf16_f32 v7, v16, v17
	global_store_dwordx4 v[32:33], v[4:7], off
	s_nop 1
	v_mov_b32_e32 v4, v134
	v_mov_b32_e32 v5, v135
	v_mov_b32_e32 v6, v136
	v_mov_b32_e32 v7, v137
	v_mov_b32_e32 v16, v138
	v_mov_b32_e32 v17, v139
	v_mov_b32_e32 v18, v140
	v_mov_b32_e32 v19, v141
	v_pk_mul_f32 v[12:13], v[12:13], v[24:25] op_sel_hi:[1,0]
	v_pk_mul_f32 v[14:15], v[14:15], v[24:25] op_sel_hi:[1,0]
	v_pk_mul_f32 v[8:9], v[8:9], v[24:25] op_sel_hi:[1,0]
	v_pk_mul_f32 v[12:13], v[12:13], v[16:17]
	s_nop 0
	v_pk_mul_f32 v[0:1], v[0:1], v[12:13]
	v_mul_f32_e32 v12, 0xbfb8aa3b, v37
	v_mul_f32_e32 v13, 0xbfb8aa3b, v41
	v_exp_f32_e32 v12, v12
	v_exp_f32_e32 v13, v13
	v_pk_mul_f32 v[14:15], v[14:15], v[18:19]
	v_pk_mul_f32 v[4:5], v[8:9], v[4:5]
	v_cvt_pk_bf16_f32 v0, v0, v1
	v_pk_add_f32 v[12:13], v[12:13], 1.0 op_sel_hi:[1,0]
	s_nop 0
	s_nop 0
	v_rcp_f32_e32 v16, v13
	s_nop 0
	v_mul_f32_e32 v13, v41, v16
	s_nop 0
	v_rcp_f32_e32 v16, v12
	s_nop 0
	v_mul_f32_e32 v12, v37, v16
	v_lshlrev_b32_e32 v16, 16, v2
	v_and_b32_e32 v2, 0xffff0000, v2
	v_pk_mul_f32 v[12:13], v[12:13], v[14:15]
	v_mul_f32_e32 v14, 0xbfb8aa3b, v16
	v_mul_f32_e32 v8, 0xbfb8aa3b, v2
	v_exp_f32_e32 v14, v14
	v_exp_f32_e32 v15, v8
	v_cvt_pk_bf16_f32 v1, v12, v13
	v_pk_add_f32 v[8:9], v[14:15], 1.0 op_sel_hi:[1,0]
	s_nop 0
	s_nop 0
	v_rcp_f32_e32 v14, v9
	s_nop 0
	v_mul_f32_e32 v9, v2, v14
	s_nop 0
	v_lshlrev_b32_e32 v14, 16, v3
	v_and_b32_e32 v15, 0xffff0000, v3
	v_rcp_f32_e32 v2, v8
	s_nop 0
	v_mul_f32_e32 v8, v16, v2
	v_mul_f32_e32 v2, 0xbfb8aa3b, v14
	v_mul_f32_e32 v3, 0xbfb8aa3b, v15
	v_exp_f32_e32 v2, v2
	v_exp_f32_e32 v3, v3
	v_pk_mul_f32 v[4:5], v[8:9], v[4:5]
	v_pk_mul_f32 v[8:9], v[10:11], v[24:25] op_sel_hi:[1,0]
	v_pk_add_f32 v[2:3], v[2:3], 1.0 op_sel_hi:[1,0]
	v_pk_mul_f32 v[6:7], v[8:9], v[6:7]
	s_nop 0
	v_rcp_f32_e32 v8, v3
	s_nop 0
	v_mul_f32_e32 v3, v15, v8
	s_nop 0
	v_rcp_f32_e32 v8, v2
	s_nop 0
	v_mul_f32_e32 v2, v14, v8
	v_pk_mul_f32 v[6:7], v[2:3], v[6:7]
	v_cvt_pk_bf16_f32 v2, v4, v5
	v_cvt_pk_bf16_f32 v3, v6, v7
	global_store_dwordx4 v[32:33], v[0:3], off offset:16
	s_barrier
	s_cbranch_scc0 .LBB0_394
.LBB0_395:
	v_readlane_b32 s88, v254, 34
	v_readlane_b32 s89, v254, 35
	v_readlane_b32 s90, v254, 36
	v_readlane_b32 s91, v254, 37
	v_readlane_b32 s92, v254, 13
	v_readlane_b32 s93, v254, 14
	v_readlane_b32 s94, v254, 15
	v_readlane_b32 s95, v254, 16
	s_mov_b64 s[0:1], 0
	s_mov_b32 s29, s61
